# RWKV scan: producer loads through SGPR bases; consumer q products software-pipelined into the next step's p chain
# speedup vs baseline: 1.1682x; 1.0082x over previous
.LBB0_1750:
	s_and_b32 s23, s22, 1
	s_mul_i32 s2, s23, 0xc000
	s_add_i32 s2, s2, 0
	v_add_u32_e32 v20, s2, v10
	s_add_i32 s2, s2, s5
	v_lshl_add_u32 v21, v1, 2, s2
	ds_read_b128 v[36:39], v20 offset:0
	ds_read_b128 v[40:43], v20 offset:8192
	ds_read_b64 v[56:57], v21 offset:40960
	ds_read_b128 v[48:51], v20 offset:24576
	ds_read_b128 v[44:47], v20 offset:16384
	ds_read_b128 v[52:55], v20 offset:32768
	s_waitcnt lgkmcnt(0)
	v_pk_mul_f32 v[22:23], v[2:3], v[36:37] op_sel:[0,0] op_sel_hi:[1,0]
	ds_read_b128 v[60:63], v20 offset:256
	v_pk_fma_f32 v[22:23], v[4:5], v[36:37], v[22:23] op_sel:[0,1,0] op_sel_hi:[1,1,1]
	ds_read_b128 v[64:67], v20 offset:8448
	v_pk_fma_f32 v[22:23], v[6:7], v[38:39], v[22:23] op_sel:[0,0,0] op_sel_hi:[1,0,1]
	ds_read_b64 v[80:81], v21 offset:41216
	v_pk_fma_f32 v[22:23], v[8:9], v[38:39], v[22:23] op_sel:[0,1,0] op_sel_hi:[1,1,1]
	ds_read_b128 v[72:75], v20 offset:24832
	ds_read_b128 v[68:71], v20 offset:16640
	ds_read_b128 v[76:79], v20 offset:33024
	v_add_f32_dpp v22, v22, v22 quad_perm:[1,0,3,2] row_mask:0xf bank_mask:0xf
	v_add_f32_dpp v23, v23, v23 quad_perm:[1,0,3,2] row_mask:0xf bank_mask:0xf
	v_pk_mul_f32 v[84:85], v[2:3], v[40:41] op_sel:[0,0] op_sel_hi:[1,0]
	v_pk_mul_f32 v[86:87], v[4:5], v[40:41] op_sel:[0,1] op_sel_hi:[1,1]
	v_add_f32_dpp v22, v22, v22 quad_perm:[2,3,0,1] row_mask:0xf bank_mask:0xf
	v_add_f32_dpp v23, v23, v23 quad_perm:[2,3,0,1] row_mask:0xf bank_mask:0xf
	v_pk_mul_f32 v[88:89], v[6:7], v[42:43] op_sel:[0,0] op_sel_hi:[1,0]
	v_pk_mul_f32 v[90:91], v[8:9], v[42:43] op_sel:[0,1] op_sel_hi:[1,1]
	v_add_f32_dpp v22, v22, v22 row_half_mirror row_mask:0xf bank_mask:0xf
	v_add_f32_dpp v23, v23, v23 row_half_mirror row_mask:0xf bank_mask:0xf
	v_pk_fma_f32 v[84:85], v[48:49], v[56:57], v[84:85] op_sel:[0,0,0] op_sel_hi:[0,1,1]
	v_pk_fma_f32 v[86:87], v[48:49], v[56:57], v[86:87] op_sel:[1,0,0] op_sel_hi:[1,1,1]
	v_add_f32_dpp v22, v22, v22 row_mirror row_mask:0xf bank_mask:0xf
	v_add_f32_dpp v23, v23, v23 row_mirror row_mask:0xf bank_mask:0xf
	v_pk_fma_f32 v[88:89], v[50:51], v[56:57], v[88:89] op_sel:[0,0,0] op_sel_hi:[0,1,1]
	v_pk_fma_f32 v[90:91], v[50:51], v[56:57], v[90:91] op_sel:[1,0,0] op_sel_hi:[1,1,1]
	v_pk_fma_f32 v[2:3], v[44:45], v[22:23], v[84:85] op_sel:[0,0,0] op_sel_hi:[0,1,1] neg_lo:[1,0,0] neg_hi:[1,0,0]
	v_pk_fma_f32 v[4:5], v[44:45], v[22:23], v[86:87] op_sel:[1,0,0] op_sel_hi:[1,1,1] neg_lo:[1,0,0] neg_hi:[1,0,0]
	v_pk_fma_f32 v[6:7], v[46:47], v[22:23], v[88:89] op_sel:[0,0,0] op_sel_hi:[0,1,1] neg_lo:[1,0,0] neg_hi:[1,0,0]
	v_pk_fma_f32 v[8:9], v[46:47], v[22:23], v[90:91] op_sel:[1,0,0] op_sel_hi:[1,1,1] neg_lo:[1,0,0] neg_hi:[1,0,0]
	s_waitcnt lgkmcnt(0)
	v_pk_mul_f32 v[22:23], v[2:3], v[60:61] op_sel:[0,0] op_sel_hi:[1,0]
	v_pk_mul_f32 v[24:25], v[2:3], v[52:53] op_sel:[0,0] op_sel_hi:[1,0]
	ds_read_b128 v[36:39], v20 offset:512
	v_pk_fma_f32 v[22:23], v[4:5], v[60:61], v[22:23] op_sel:[0,1,0] op_sel_hi:[1,1,1]
	v_pk_mul_f32 v[84:85], v[4:5], v[52:53] op_sel:[0,1] op_sel_hi:[1,1]
	ds_read_b128 v[40:43], v20 offset:8704
	v_pk_fma_f32 v[22:23], v[6:7], v[62:63], v[22:23] op_sel:[0,0,0] op_sel_hi:[1,0,1]
	v_pk_fma_f32 v[24:25], v[6:7], v[54:55], v[24:25] op_sel:[0,0,0] op_sel_hi:[1,0,1]
	ds_read_b64 v[56:57], v21 offset:41472
	v_pk_fma_f32 v[22:23], v[8:9], v[62:63], v[22:23] op_sel:[0,1,0] op_sel_hi:[1,1,1]
	v_pk_fma_f32 v[84:85], v[8:9], v[54:55], v[84:85] op_sel:[0,1,0] op_sel_hi:[1,1,1]
	ds_read_b128 v[48:51], v20 offset:25088
	v_pk_add_f32 v[24:25], v[24:25], v[84:85]
	ds_read_b128 v[44:47], v20 offset:16896
	ds_read_b128 v[52:55], v20 offset:33280
	v_add_f32_dpp v22, v22, v22 quad_perm:[1,0,3,2] row_mask:0xf bank_mask:0xf
	v_add_f32_dpp v23, v23, v23 quad_perm:[1,0,3,2] row_mask:0xf bank_mask:0xf
	v_pk_mul_f32 v[84:85], v[2:3], v[64:65] op_sel:[0,0] op_sel_hi:[1,0]
	v_pk_mul_f32 v[86:87], v[4:5], v[64:65] op_sel:[0,1] op_sel_hi:[1,1]
	v_add_f32_dpp v22, v22, v22 quad_perm:[2,3,0,1] row_mask:0xf bank_mask:0xf
	v_add_f32_dpp v23, v23, v23 quad_perm:[2,3,0,1] row_mask:0xf bank_mask:0xf
	v_pk_mul_f32 v[88:89], v[6:7], v[66:67] op_sel:[0,0] op_sel_hi:[1,0]
	v_pk_mul_f32 v[90:91], v[8:9], v[66:67] op_sel:[0,1] op_sel_hi:[1,1]
	v_add_f32_dpp v22, v22, v22 row_half_mirror row_mask:0xf bank_mask:0xf
	v_add_f32_dpp v23, v23, v23 row_half_mirror row_mask:0xf bank_mask:0xf
	v_pk_fma_f32 v[84:85], v[72:73], v[80:81], v[84:85] op_sel:[0,0,0] op_sel_hi:[0,1,1]
	v_pk_fma_f32 v[86:87], v[72:73], v[80:81], v[86:87] op_sel:[1,0,0] op_sel_hi:[1,1,1]
	v_add_f32_dpp v22, v22, v22 row_mirror row_mask:0xf bank_mask:0xf
	v_add_f32_dpp v23, v23, v23 row_mirror row_mask:0xf bank_mask:0xf
	v_pk_fma_f32 v[88:89], v[74:75], v[80:81], v[88:89] op_sel:[0,0,0] op_sel_hi:[0,1,1]
	v_pk_fma_f32 v[90:91], v[74:75], v[80:81], v[90:91] op_sel:[1,0,0] op_sel_hi:[1,1,1]
	v_pk_fma_f32 v[2:3], v[68:69], v[22:23], v[84:85] op_sel:[0,0,0] op_sel_hi:[0,1,1] neg_lo:[1,0,0] neg_hi:[1,0,0]
	v_pk_fma_f32 v[4:5], v[68:69], v[22:23], v[86:87] op_sel:[1,0,0] op_sel_hi:[1,1,1] neg_lo:[1,0,0] neg_hi:[1,0,0]
	v_pk_fma_f32 v[6:7], v[70:71], v[22:23], v[88:89] op_sel:[0,0,0] op_sel_hi:[0,1,1] neg_lo:[1,0,0] neg_hi:[1,0,0]
	v_pk_fma_f32 v[8:9], v[70:71], v[22:23], v[90:91] op_sel:[1,0,0] op_sel_hi:[1,1,1] neg_lo:[1,0,0] neg_hi:[1,0,0]
	s_waitcnt lgkmcnt(0)
	v_pk_mul_f32 v[22:23], v[2:3], v[36:37] op_sel:[0,0] op_sel_hi:[1,0]
	v_pk_mul_f32 v[26:27], v[2:3], v[76:77] op_sel:[0,0] op_sel_hi:[1,0]
	ds_read_b128 v[60:63], v20 offset:768
	v_pk_fma_f32 v[22:23], v[4:5], v[36:37], v[22:23] op_sel:[0,1,0] op_sel_hi:[1,1,1]
	v_pk_mul_f32 v[84:85], v[4:5], v[76:77] op_sel:[0,1] op_sel_hi:[1,1]
	ds_read_b128 v[64:67], v20 offset:8960
	v_pk_fma_f32 v[22:23], v[6:7], v[38:39], v[22:23] op_sel:[0,0,0] op_sel_hi:[1,0,1]
	v_pk_fma_f32 v[26:27], v[6:7], v[78:79], v[26:27] op_sel:[0,0,0] op_sel_hi:[1,0,1]
	ds_read_b64 v[80:81], v21 offset:41728
	v_pk_fma_f32 v[22:23], v[8:9], v[38:39], v[22:23] op_sel:[0,1,0] op_sel_hi:[1,1,1]
	v_pk_fma_f32 v[84:85], v[8:9], v[78:79], v[84:85] op_sel:[0,1,0] op_sel_hi:[1,1,1]
	ds_read_b128 v[72:75], v20 offset:25344
	v_pk_add_f32 v[26:27], v[26:27], v[84:85]
	ds_read_b128 v[68:71], v20 offset:17152
	ds_read_b128 v[76:79], v20 offset:33536
	v_add_f32_dpp v24, v24, v24 row_ror:12 row_mask:0xf bank_mask:0x5
	v_add_f32_dpp v25, v25, v25 row_ror:4 row_mask:0xf bank_mask:0xa
	v_add_f32_dpp v22, v22, v22 quad_perm:[1,0,3,2] row_mask:0xf bank_mask:0xf
	v_add_f32_dpp v23, v23, v23 quad_perm:[1,0,3,2] row_mask:0xf bank_mask:0xf
	v_pk_mul_f32 v[84:85], v[2:3], v[40:41] op_sel:[0,0] op_sel_hi:[1,0]
	v_pk_mul_f32 v[86:87], v[4:5], v[40:41] op_sel:[0,1] op_sel_hi:[1,1]
	v_mov_b32_dpp v24, v25 quad_perm:[0,1,2,3] row_mask:0xf bank_mask:0xa
	v_add_f32_dpp v22, v22, v22 quad_perm:[2,3,0,1] row_mask:0xf bank_mask:0xf
	v_add_f32_dpp v23, v23, v23 quad_perm:[2,3,0,1] row_mask:0xf bank_mask:0xf
	v_pk_mul_f32 v[88:89], v[6:7], v[42:43] op_sel:[0,0] op_sel_hi:[1,0]
	v_pk_mul_f32 v[90:91], v[8:9], v[42:43] op_sel:[0,1] op_sel_hi:[1,1]
	v_add_f32_dpp v24, v24, v24 row_ror:8 row_mask:0xf bank_mask:0xf
	v_add_f32_dpp v22, v22, v22 row_half_mirror row_mask:0xf bank_mask:0xf
	v_add_f32_dpp v23, v23, v23 row_half_mirror row_mask:0xf bank_mask:0xf
	v_pk_fma_f32 v[84:85], v[48:49], v[56:57], v[84:85] op_sel:[0,0,0] op_sel_hi:[0,1,1]
	v_pk_fma_f32 v[86:87], v[48:49], v[56:57], v[86:87] op_sel:[1,0,0] op_sel_hi:[1,1,1]
	v_add_f32_dpp v24, v24, v24 quad_perm:[1,0,3,2] row_mask:0xf bank_mask:0xf
	v_add_f32_dpp v22, v22, v22 row_mirror row_mask:0xf bank_mask:0xf
	v_add_f32_dpp v23, v23, v23 row_mirror row_mask:0xf bank_mask:0xf
	v_pk_fma_f32 v[88:89], v[50:51], v[56:57], v[88:89] op_sel:[0,0,0] op_sel_hi:[0,1,1]
	v_pk_fma_f32 v[90:91], v[50:51], v[56:57], v[90:91] op_sel:[1,0,0] op_sel_hi:[1,1,1]
	v_add_f32_dpp v24, v24, v24 quad_perm:[2,3,0,1] row_mask:0xf bank_mask:0xf
	v_cndmask_b32_e64 v30, 0, v24, s[0:1]
	v_pk_fma_f32 v[2:3], v[44:45], v[22:23], v[84:85] op_sel:[0,0,0] op_sel_hi:[0,1,1] neg_lo:[1,0,0] neg_hi:[1,0,0]
	v_pk_fma_f32 v[4:5], v[44:45], v[22:23], v[86:87] op_sel:[1,0,0] op_sel_hi:[1,1,1] neg_lo:[1,0,0] neg_hi:[1,0,0]
	v_pk_fma_f32 v[6:7], v[46:47], v[22:23], v[88:89] op_sel:[0,0,0] op_sel_hi:[0,1,1] neg_lo:[1,0,0] neg_hi:[1,0,0]
	v_pk_fma_f32 v[8:9], v[46:47], v[22:23], v[90:91] op_sel:[1,0,0] op_sel_hi:[1,1,1] neg_lo:[1,0,0] neg_hi:[1,0,0]
	s_waitcnt lgkmcnt(0)
	v_pk_mul_f32 v[22:23], v[2:3], v[60:61] op_sel:[0,0] op_sel_hi:[1,0]
	v_pk_mul_f32 v[24:25], v[2:3], v[52:53] op_sel:[0,0] op_sel_hi:[1,0]
	ds_read_b128 v[36:39], v20 offset:1024
	v_pk_fma_f32 v[22:23], v[4:5], v[60:61], v[22:23] op_sel:[0,1,0] op_sel_hi:[1,1,1]
	v_pk_mul_f32 v[84:85], v[4:5], v[52:53] op_sel:[0,1] op_sel_hi:[1,1]
	ds_read_b128 v[40:43], v20 offset:9216
	v_pk_fma_f32 v[22:23], v[6:7], v[62:63], v[22:23] op_sel:[0,0,0] op_sel_hi:[1,0,1]
	v_pk_fma_f32 v[24:25], v[6:7], v[54:55], v[24:25] op_sel:[0,0,0] op_sel_hi:[1,0,1]
	ds_read_b64 v[56:57], v21 offset:41984
	v_pk_fma_f32 v[22:23], v[8:9], v[62:63], v[22:23] op_sel:[0,1,0] op_sel_hi:[1,1,1]
	v_pk_fma_f32 v[84:85], v[8:9], v[54:55], v[84:85] op_sel:[0,1,0] op_sel_hi:[1,1,1]
	ds_read_b128 v[48:51], v20 offset:25600
	v_pk_add_f32 v[24:25], v[24:25], v[84:85]
	ds_read_b128 v[44:47], v20 offset:17408
	ds_read_b128 v[52:55], v20 offset:33792
	v_add_f32_dpp v26, v26, v26 row_ror:12 row_mask:0xf bank_mask:0x5
	v_add_f32_dpp v27, v27, v27 row_ror:4 row_mask:0xf bank_mask:0xa
	v_add_f32_dpp v22, v22, v22 quad_perm:[1,0,3,2] row_mask:0xf bank_mask:0xf
	v_add_f32_dpp v23, v23, v23 quad_perm:[1,0,3,2] row_mask:0xf bank_mask:0xf
	v_pk_mul_f32 v[84:85], v[2:3], v[64:65] op_sel:[0,0] op_sel_hi:[1,0]
	v_pk_mul_f32 v[86:87], v[4:5], v[64:65] op_sel:[0,1] op_sel_hi:[1,1]
	v_mov_b32_dpp v26, v27 quad_perm:[0,1,2,3] row_mask:0xf bank_mask:0xa
	v_add_f32_dpp v22, v22, v22 quad_perm:[2,3,0,1] row_mask:0xf bank_mask:0xf
	v_add_f32_dpp v23, v23, v23 quad_perm:[2,3,0,1] row_mask:0xf bank_mask:0xf
	v_pk_mul_f32 v[88:89], v[6:7], v[66:67] op_sel:[0,0] op_sel_hi:[1,0]
	v_pk_mul_f32 v[90:91], v[8:9], v[66:67] op_sel:[0,1] op_sel_hi:[1,1]
	v_add_f32_dpp v26, v26, v26 row_ror:8 row_mask:0xf bank_mask:0xf
	v_add_f32_dpp v22, v22, v22 row_half_mirror row_mask:0xf bank_mask:0xf
	v_add_f32_dpp v23, v23, v23 row_half_mirror row_mask:0xf bank_mask:0xf
	v_pk_fma_f32 v[84:85], v[72:73], v[80:81], v[84:85] op_sel:[0,0,0] op_sel_hi:[0,1,1]
	v_pk_fma_f32 v[86:87], v[72:73], v[80:81], v[86:87] op_sel:[1,0,0] op_sel_hi:[1,1,1]
	v_add_f32_dpp v26, v26, v26 quad_perm:[1,0,3,2] row_mask:0xf bank_mask:0xf
	v_add_f32_dpp v22, v22, v22 row_mirror row_mask:0xf bank_mask:0xf
	v_add_f32_dpp v23, v23, v23 row_mirror row_mask:0xf bank_mask:0xf
	v_pk_fma_f32 v[88:89], v[74:75], v[80:81], v[88:89] op_sel:[0,0,0] op_sel_hi:[0,1,1]
	v_pk_fma_f32 v[90:91], v[74:75], v[80:81], v[90:91] op_sel:[1,0,0] op_sel_hi:[1,1,1]
	v_add_f32_dpp v26, v26, v26 quad_perm:[2,3,0,1] row_mask:0xf bank_mask:0xf
	v_cndmask_b32_e64 v30, v30, v26, s[6:7]
	v_pk_fma_f32 v[2:3], v[68:69], v[22:23], v[84:85] op_sel:[0,0,0] op_sel_hi:[0,1,1] neg_lo:[1,0,0] neg_hi:[1,0,0]
	v_pk_fma_f32 v[4:5], v[68:69], v[22:23], v[86:87] op_sel:[1,0,0] op_sel_hi:[1,1,1] neg_lo:[1,0,0] neg_hi:[1,0,0]
	v_pk_fma_f32 v[6:7], v[70:71], v[22:23], v[88:89] op_sel:[0,0,0] op_sel_hi:[0,1,1] neg_lo:[1,0,0] neg_hi:[1,0,0]
	v_pk_fma_f32 v[8:9], v[70:71], v[22:23], v[90:91] op_sel:[1,0,0] op_sel_hi:[1,1,1] neg_lo:[1,0,0] neg_hi:[1,0,0]
	s_waitcnt lgkmcnt(0)
	v_pk_mul_f32 v[22:23], v[2:3], v[36:37] op_sel:[0,0] op_sel_hi:[1,0]
	v_pk_mul_f32 v[26:27], v[2:3], v[76:77] op_sel:[0,0] op_sel_hi:[1,0]
	ds_read_b128 v[60:63], v20 offset:1280
	v_pk_fma_f32 v[22:23], v[4:5], v[36:37], v[22:23] op_sel:[0,1,0] op_sel_hi:[1,1,1]
	v_pk_mul_f32 v[84:85], v[4:5], v[76:77] op_sel:[0,1] op_sel_hi:[1,1]
	ds_read_b128 v[64:67], v20 offset:9472
	v_pk_fma_f32 v[22:23], v[6:7], v[38:39], v[22:23] op_sel:[0,0,0] op_sel_hi:[1,0,1]
	v_pk_fma_f32 v[26:27], v[6:7], v[78:79], v[26:27] op_sel:[0,0,0] op_sel_hi:[1,0,1]
	ds_read_b64 v[80:81], v21 offset:42240
	v_pk_fma_f32 v[22:23], v[8:9], v[38:39], v[22:23] op_sel:[0,1,0] op_sel_hi:[1,1,1]
	v_pk_fma_f32 v[84:85], v[8:9], v[78:79], v[84:85] op_sel:[0,1,0] op_sel_hi:[1,1,1]
	ds_read_b128 v[72:75], v20 offset:25856
	v_pk_add_f32 v[26:27], v[26:27], v[84:85]
	ds_read_b128 v[68:71], v20 offset:17664
	ds_read_b128 v[76:79], v20 offset:34048
	v_add_f32_dpp v24, v24, v24 row_ror:12 row_mask:0xf bank_mask:0x5
	v_add_f32_dpp v25, v25, v25 row_ror:4 row_mask:0xf bank_mask:0xa
	v_add_f32_dpp v22, v22, v22 quad_perm:[1,0,3,2] row_mask:0xf bank_mask:0xf
	v_add_f32_dpp v23, v23, v23 quad_perm:[1,0,3,2] row_mask:0xf bank_mask:0xf
	v_pk_mul_f32 v[84:85], v[2:3], v[40:41] op_sel:[0,0] op_sel_hi:[1,0]
	v_pk_mul_f32 v[86:87], v[4:5], v[40:41] op_sel:[0,1] op_sel_hi:[1,1]
	v_mov_b32_dpp v24, v25 quad_perm:[0,1,2,3] row_mask:0xf bank_mask:0xa
	v_add_f32_dpp v22, v22, v22 quad_perm:[2,3,0,1] row_mask:0xf bank_mask:0xf
	v_add_f32_dpp v23, v23, v23 quad_perm:[2,3,0,1] row_mask:0xf bank_mask:0xf
	v_pk_mul_f32 v[88:89], v[6:7], v[42:43] op_sel:[0,0] op_sel_hi:[1,0]
	v_pk_mul_f32 v[90:91], v[8:9], v[42:43] op_sel:[0,1] op_sel_hi:[1,1]
	v_add_f32_dpp v24, v24, v24 row_ror:8 row_mask:0xf bank_mask:0xf
	v_add_f32_dpp v22, v22, v22 row_half_mirror row_mask:0xf bank_mask:0xf
	v_add_f32_dpp v23, v23, v23 row_half_mirror row_mask:0xf bank_mask:0xf
	v_pk_fma_f32 v[84:85], v[48:49], v[56:57], v[84:85] op_sel:[0,0,0] op_sel_hi:[0,1,1]
	v_pk_fma_f32 v[86:87], v[48:49], v[56:57], v[86:87] op_sel:[1,0,0] op_sel_hi:[1,1,1]
	v_add_f32_dpp v24, v24, v24 quad_perm:[1,0,3,2] row_mask:0xf bank_mask:0xf
	v_add_f32_dpp v22, v22, v22 row_mirror row_mask:0xf bank_mask:0xf
	v_add_f32_dpp v23, v23, v23 row_mirror row_mask:0xf bank_mask:0xf
	v_pk_fma_f32 v[88:89], v[50:51], v[56:57], v[88:89] op_sel:[0,0,0] op_sel_hi:[0,1,1]
	v_pk_fma_f32 v[90:91], v[50:51], v[56:57], v[90:91] op_sel:[1,0,0] op_sel_hi:[1,1,1]
	v_add_f32_dpp v24, v24, v24 quad_perm:[2,3,0,1] row_mask:0xf bank_mask:0xf
	v_cndmask_b32_e64 v30, v30, v24, s[8:9]
	v_pk_fma_f32 v[2:3], v[44:45], v[22:23], v[84:85] op_sel:[0,0,0] op_sel_hi:[0,1,1] neg_lo:[1,0,0] neg_hi:[1,0,0]
	v_pk_fma_f32 v[4:5], v[44:45], v[22:23], v[86:87] op_sel:[1,0,0] op_sel_hi:[1,1,1] neg_lo:[1,0,0] neg_hi:[1,0,0]
	v_pk_fma_f32 v[6:7], v[46:47], v[22:23], v[88:89] op_sel:[0,0,0] op_sel_hi:[0,1,1] neg_lo:[1,0,0] neg_hi:[1,0,0]
	v_pk_fma_f32 v[8:9], v[46:47], v[22:23], v[90:91] op_sel:[1,0,0] op_sel_hi:[1,1,1] neg_lo:[1,0,0] neg_hi:[1,0,0]
	s_waitcnt lgkmcnt(0)
	v_pk_mul_f32 v[22:23], v[2:3], v[60:61] op_sel:[0,0] op_sel_hi:[1,0]
	v_pk_mul_f32 v[24:25], v[2:3], v[52:53] op_sel:[0,0] op_sel_hi:[1,0]
	ds_read_b128 v[36:39], v20 offset:1536
	v_pk_fma_f32 v[22:23], v[4:5], v[60:61], v[22:23] op_sel:[0,1,0] op_sel_hi:[1,1,1]
	v_pk_mul_f32 v[84:85], v[4:5], v[52:53] op_sel:[0,1] op_sel_hi:[1,1]
	ds_read_b128 v[40:43], v20 offset:9728
	v_pk_fma_f32 v[22:23], v[6:7], v[62:63], v[22:23] op_sel:[0,0,0] op_sel_hi:[1,0,1]
	v_pk_fma_f32 v[24:25], v[6:7], v[54:55], v[24:25] op_sel:[0,0,0] op_sel_hi:[1,0,1]
	ds_read_b64 v[56:57], v21 offset:42496
	v_pk_fma_f32 v[22:23], v[8:9], v[62:63], v[22:23] op_sel:[0,1,0] op_sel_hi:[1,1,1]
	v_pk_fma_f32 v[84:85], v[8:9], v[54:55], v[84:85] op_sel:[0,1,0] op_sel_hi:[1,1,1]
	ds_read_b128 v[48:51], v20 offset:26112
	v_pk_add_f32 v[24:25], v[24:25], v[84:85]
	ds_read_b128 v[44:47], v20 offset:17920
	ds_read_b128 v[52:55], v20 offset:34304
	v_add_f32_dpp v26, v26, v26 row_ror:12 row_mask:0xf bank_mask:0x5
	v_add_f32_dpp v27, v27, v27 row_ror:4 row_mask:0xf bank_mask:0xa
	v_add_f32_dpp v22, v22, v22 quad_perm:[1,0,3,2] row_mask:0xf bank_mask:0xf
	v_add_f32_dpp v23, v23, v23 quad_perm:[1,0,3,2] row_mask:0xf bank_mask:0xf
	v_pk_mul_f32 v[84:85], v[2:3], v[64:65] op_sel:[0,0] op_sel_hi:[1,0]
	v_pk_mul_f32 v[86:87], v[4:5], v[64:65] op_sel:[0,1] op_sel_hi:[1,1]
	v_mov_b32_dpp v26, v27 quad_perm:[0,1,2,3] row_mask:0xf bank_mask:0xa
	v_add_f32_dpp v22, v22, v22 quad_perm:[2,3,0,1] row_mask:0xf bank_mask:0xf
	v_add_f32_dpp v23, v23, v23 quad_perm:[2,3,0,1] row_mask:0xf bank_mask:0xf
	v_pk_mul_f32 v[88:89], v[6:7], v[66:67] op_sel:[0,0] op_sel_hi:[1,0]
	v_pk_mul_f32 v[90:91], v[8:9], v[66:67] op_sel:[0,1] op_sel_hi:[1,1]
	v_add_f32_dpp v26, v26, v26 row_ror:8 row_mask:0xf bank_mask:0xf
	v_add_f32_dpp v22, v22, v22 row_half_mirror row_mask:0xf bank_mask:0xf
	v_add_f32_dpp v23, v23, v23 row_half_mirror row_mask:0xf bank_mask:0xf
	v_pk_fma_f32 v[84:85], v[72:73], v[80:81], v[84:85] op_sel:[0,0,0] op_sel_hi:[0,1,1]
	v_pk_fma_f32 v[86:87], v[72:73], v[80:81], v[86:87] op_sel:[1,0,0] op_sel_hi:[1,1,1]
	v_add_f32_dpp v26, v26, v26 quad_perm:[1,0,3,2] row_mask:0xf bank_mask:0xf
	v_add_f32_dpp v22, v22, v22 row_mirror row_mask:0xf bank_mask:0xf
	v_add_f32_dpp v23, v23, v23 row_mirror row_mask:0xf bank_mask:0xf
	v_pk_fma_f32 v[88:89], v[74:75], v[80:81], v[88:89] op_sel:[0,0,0] op_sel_hi:[0,1,1]
	v_pk_fma_f32 v[90:91], v[74:75], v[80:81], v[90:91] op_sel:[1,0,0] op_sel_hi:[1,1,1]
	v_add_f32_dpp v26, v26, v26 quad_perm:[2,3,0,1] row_mask:0xf bank_mask:0xf
	v_cndmask_b32_e64 v30, v30, v26, s[10:11]
	v_pk_fma_f32 v[2:3], v[68:69], v[22:23], v[84:85] op_sel:[0,0,0] op_sel_hi:[0,1,1] neg_lo:[1,0,0] neg_hi:[1,0,0]
	v_pk_fma_f32 v[4:5], v[68:69], v[22:23], v[86:87] op_sel:[1,0,0] op_sel_hi:[1,1,1] neg_lo:[1,0,0] neg_hi:[1,0,0]
	v_pk_fma_f32 v[6:7], v[70:71], v[22:23], v[88:89] op_sel:[0,0,0] op_sel_hi:[0,1,1] neg_lo:[1,0,0] neg_hi:[1,0,0]
	v_pk_fma_f32 v[8:9], v[70:71], v[22:23], v[90:91] op_sel:[1,0,0] op_sel_hi:[1,1,1] neg_lo:[1,0,0] neg_hi:[1,0,0]
	s_waitcnt lgkmcnt(0)
	v_pk_mul_f32 v[22:23], v[2:3], v[36:37] op_sel:[0,0] op_sel_hi:[1,0]
	v_pk_mul_f32 v[26:27], v[2:3], v[76:77] op_sel:[0,0] op_sel_hi:[1,0]
	ds_read_b128 v[60:63], v20 offset:1792
	v_pk_fma_f32 v[22:23], v[4:5], v[36:37], v[22:23] op_sel:[0,1,0] op_sel_hi:[1,1,1]
	v_pk_mul_f32 v[84:85], v[4:5], v[76:77] op_sel:[0,1] op_sel_hi:[1,1]
	ds_read_b128 v[64:67], v20 offset:9984
	v_pk_fma_f32 v[22:23], v[6:7], v[38:39], v[22:23] op_sel:[0,0,0] op_sel_hi:[1,0,1]
	v_pk_fma_f32 v[26:27], v[6:7], v[78:79], v[26:27] op_sel:[0,0,0] op_sel_hi:[1,0,1]
	ds_read_b64 v[80:81], v21 offset:42752
	v_pk_fma_f32 v[22:23], v[8:9], v[38:39], v[22:23] op_sel:[0,1,0] op_sel_hi:[1,1,1]
	v_pk_fma_f32 v[84:85], v[8:9], v[78:79], v[84:85] op_sel:[0,1,0] op_sel_hi:[1,1,1]
	ds_read_b128 v[72:75], v20 offset:26368
	v_pk_add_f32 v[26:27], v[26:27], v[84:85]
	ds_read_b128 v[68:71], v20 offset:18176
	ds_read_b128 v[76:79], v20 offset:34560
	v_add_f32_dpp v24, v24, v24 row_ror:12 row_mask:0xf bank_mask:0x5
	v_add_f32_dpp v25, v25, v25 row_ror:4 row_mask:0xf bank_mask:0xa
	v_add_f32_dpp v22, v22, v22 quad_perm:[1,0,3,2] row_mask:0xf bank_mask:0xf
	v_add_f32_dpp v23, v23, v23 quad_perm:[1,0,3,2] row_mask:0xf bank_mask:0xf
	v_pk_mul_f32 v[84:85], v[2:3], v[40:41] op_sel:[0,0] op_sel_hi:[1,0]
	v_pk_mul_f32 v[86:87], v[4:5], v[40:41] op_sel:[0,1] op_sel_hi:[1,1]
	v_mov_b32_dpp v24, v25 quad_perm:[0,1,2,3] row_mask:0xf bank_mask:0xa
	v_add_f32_dpp v22, v22, v22 quad_perm:[2,3,0,1] row_mask:0xf bank_mask:0xf
	v_add_f32_dpp v23, v23, v23 quad_perm:[2,3,0,1] row_mask:0xf bank_mask:0xf
	v_pk_mul_f32 v[88:89], v[6:7], v[42:43] op_sel:[0,0] op_sel_hi:[1,0]
	v_pk_mul_f32 v[90:91], v[8:9], v[42:43] op_sel:[0,1] op_sel_hi:[1,1]
	v_add_f32_dpp v24, v24, v24 row_ror:8 row_mask:0xf bank_mask:0xf
	v_add_f32_dpp v22, v22, v22 row_half_mirror row_mask:0xf bank_mask:0xf
	v_add_f32_dpp v23, v23, v23 row_half_mirror row_mask:0xf bank_mask:0xf
	v_pk_fma_f32 v[84:85], v[48:49], v[56:57], v[84:85] op_sel:[0,0,0] op_sel_hi:[0,1,1]
	v_pk_fma_f32 v[86:87], v[48:49], v[56:57], v[86:87] op_sel:[1,0,0] op_sel_hi:[1,1,1]
	v_add_f32_dpp v24, v24, v24 quad_perm:[1,0,3,2] row_mask:0xf bank_mask:0xf
	v_add_f32_dpp v22, v22, v22 row_mirror row_mask:0xf bank_mask:0xf
	v_add_f32_dpp v23, v23, v23 row_mirror row_mask:0xf bank_mask:0xf
	v_pk_fma_f32 v[88:89], v[50:51], v[56:57], v[88:89] op_sel:[0,0,0] op_sel_hi:[0,1,1]
	v_pk_fma_f32 v[90:91], v[50:51], v[56:57], v[90:91] op_sel:[1,0,0] op_sel_hi:[1,1,1]
	v_add_f32_dpp v24, v24, v24 quad_perm:[2,3,0,1] row_mask:0xf bank_mask:0xf
	v_cndmask_b32_e64 v30, v30, v24, s[12:13]
	v_pk_fma_f32 v[2:3], v[44:45], v[22:23], v[84:85] op_sel:[0,0,0] op_sel_hi:[0,1,1] neg_lo:[1,0,0] neg_hi:[1,0,0]
	v_pk_fma_f32 v[4:5], v[44:45], v[22:23], v[86:87] op_sel:[1,0,0] op_sel_hi:[1,1,1] neg_lo:[1,0,0] neg_hi:[1,0,0]
	v_pk_fma_f32 v[6:7], v[46:47], v[22:23], v[88:89] op_sel:[0,0,0] op_sel_hi:[0,1,1] neg_lo:[1,0,0] neg_hi:[1,0,0]
	v_pk_fma_f32 v[8:9], v[46:47], v[22:23], v[90:91] op_sel:[1,0,0] op_sel_hi:[1,1,1] neg_lo:[1,0,0] neg_hi:[1,0,0]
	s_waitcnt lgkmcnt(0)
	v_pk_mul_f32 v[22:23], v[2:3], v[60:61] op_sel:[0,0] op_sel_hi:[1,0]
	v_pk_mul_f32 v[24:25], v[2:3], v[52:53] op_sel:[0,0] op_sel_hi:[1,0]
	ds_read_b128 v[36:39], v20 offset:2048
	v_pk_fma_f32 v[22:23], v[4:5], v[60:61], v[22:23] op_sel:[0,1,0] op_sel_hi:[1,1,1]
	v_pk_mul_f32 v[84:85], v[4:5], v[52:53] op_sel:[0,1] op_sel_hi:[1,1]
	ds_read_b128 v[40:43], v20 offset:10240
	v_pk_fma_f32 v[22:23], v[6:7], v[62:63], v[22:23] op_sel:[0,0,0] op_sel_hi:[1,0,1]
	v_pk_fma_f32 v[24:25], v[6:7], v[54:55], v[24:25] op_sel:[0,0,0] op_sel_hi:[1,0,1]
	ds_read_b64 v[56:57], v21 offset:43008
	v_pk_fma_f32 v[22:23], v[8:9], v[62:63], v[22:23] op_sel:[0,1,0] op_sel_hi:[1,1,1]
	v_pk_fma_f32 v[84:85], v[8:9], v[54:55], v[84:85] op_sel:[0,1,0] op_sel_hi:[1,1,1]
	ds_read_b128 v[48:51], v20 offset:26624
	v_pk_add_f32 v[24:25], v[24:25], v[84:85]
	ds_read_b128 v[44:47], v20 offset:18432
	ds_read_b128 v[52:55], v20 offset:34816
	v_add_f32_dpp v26, v26, v26 row_ror:12 row_mask:0xf bank_mask:0x5
	v_add_f32_dpp v27, v27, v27 row_ror:4 row_mask:0xf bank_mask:0xa
	v_add_f32_dpp v22, v22, v22 quad_perm:[1,0,3,2] row_mask:0xf bank_mask:0xf
	v_add_f32_dpp v23, v23, v23 quad_perm:[1,0,3,2] row_mask:0xf bank_mask:0xf
	v_pk_mul_f32 v[84:85], v[2:3], v[64:65] op_sel:[0,0] op_sel_hi:[1,0]
	v_pk_mul_f32 v[86:87], v[4:5], v[64:65] op_sel:[0,1] op_sel_hi:[1,1]
	v_mov_b32_dpp v26, v27 quad_perm:[0,1,2,3] row_mask:0xf bank_mask:0xa
	v_add_f32_dpp v22, v22, v22 quad_perm:[2,3,0,1] row_mask:0xf bank_mask:0xf
	v_add_f32_dpp v23, v23, v23 quad_perm:[2,3,0,1] row_mask:0xf bank_mask:0xf
	v_pk_mul_f32 v[88:89], v[6:7], v[66:67] op_sel:[0,0] op_sel_hi:[1,0]
	v_pk_mul_f32 v[90:91], v[8:9], v[66:67] op_sel:[0,1] op_sel_hi:[1,1]
	v_add_f32_dpp v26, v26, v26 row_ror:8 row_mask:0xf bank_mask:0xf
	v_add_f32_dpp v22, v22, v22 row_half_mirror row_mask:0xf bank_mask:0xf
	v_add_f32_dpp v23, v23, v23 row_half_mirror row_mask:0xf bank_mask:0xf
	v_pk_fma_f32 v[84:85], v[72:73], v[80:81], v[84:85] op_sel:[0,0,0] op_sel_hi:[0,1,1]
	v_pk_fma_f32 v[86:87], v[72:73], v[80:81], v[86:87] op_sel:[1,0,0] op_sel_hi:[1,1,1]
	v_add_f32_dpp v26, v26, v26 quad_perm:[1,0,3,2] row_mask:0xf bank_mask:0xf
	v_add_f32_dpp v22, v22, v22 row_mirror row_mask:0xf bank_mask:0xf
	v_add_f32_dpp v23, v23, v23 row_mirror row_mask:0xf bank_mask:0xf
	v_pk_fma_f32 v[88:89], v[74:75], v[80:81], v[88:89] op_sel:[0,0,0] op_sel_hi:[0,1,1]
	v_pk_fma_f32 v[90:91], v[74:75], v[80:81], v[90:91] op_sel:[1,0,0] op_sel_hi:[1,1,1]
	v_add_f32_dpp v26, v26, v26 quad_perm:[2,3,0,1] row_mask:0xf bank_mask:0xf
	v_cndmask_b32_e64 v30, v30, v26, s[14:15]
	v_pk_fma_f32 v[2:3], v[68:69], v[22:23], v[84:85] op_sel:[0,0,0] op_sel_hi:[0,1,1] neg_lo:[1,0,0] neg_hi:[1,0,0]
	v_pk_fma_f32 v[4:5], v[68:69], v[22:23], v[86:87] op_sel:[1,0,0] op_sel_hi:[1,1,1] neg_lo:[1,0,0] neg_hi:[1,0,0]
	v_pk_fma_f32 v[6:7], v[70:71], v[22:23], v[88:89] op_sel:[0,0,0] op_sel_hi:[0,1,1] neg_lo:[1,0,0] neg_hi:[1,0,0]
	v_pk_fma_f32 v[8:9], v[70:71], v[22:23], v[90:91] op_sel:[1,0,0] op_sel_hi:[1,1,1] neg_lo:[1,0,0] neg_hi:[1,0,0]
	s_waitcnt lgkmcnt(0)
	v_pk_mul_f32 v[22:23], v[2:3], v[36:37] op_sel:[0,0] op_sel_hi:[1,0]
	v_pk_mul_f32 v[26:27], v[2:3], v[76:77] op_sel:[0,0] op_sel_hi:[1,0]
	ds_read_b128 v[60:63], v20 offset:2304
	v_pk_fma_f32 v[22:23], v[4:5], v[36:37], v[22:23] op_sel:[0,1,0] op_sel_hi:[1,1,1]
	v_pk_mul_f32 v[84:85], v[4:5], v[76:77] op_sel:[0,1] op_sel_hi:[1,1]
	ds_read_b128 v[64:67], v20 offset:10496
	v_pk_fma_f32 v[22:23], v[6:7], v[38:39], v[22:23] op_sel:[0,0,0] op_sel_hi:[1,0,1]
	v_pk_fma_f32 v[26:27], v[6:7], v[78:79], v[26:27] op_sel:[0,0,0] op_sel_hi:[1,0,1]
	ds_read_b64 v[80:81], v21 offset:43264
	v_pk_fma_f32 v[22:23], v[8:9], v[38:39], v[22:23] op_sel:[0,1,0] op_sel_hi:[1,1,1]
	v_pk_fma_f32 v[84:85], v[8:9], v[78:79], v[84:85] op_sel:[0,1,0] op_sel_hi:[1,1,1]
	ds_read_b128 v[72:75], v20 offset:26880
	v_pk_add_f32 v[26:27], v[26:27], v[84:85]
	ds_read_b128 v[68:71], v20 offset:18688
	ds_read_b128 v[76:79], v20 offset:35072
	v_add_f32_dpp v24, v24, v24 row_ror:12 row_mask:0xf bank_mask:0x5
	v_add_f32_dpp v25, v25, v25 row_ror:4 row_mask:0xf bank_mask:0xa
	v_add_f32_dpp v22, v22, v22 quad_perm:[1,0,3,2] row_mask:0xf bank_mask:0xf
	v_add_f32_dpp v23, v23, v23 quad_perm:[1,0,3,2] row_mask:0xf bank_mask:0xf
	v_pk_mul_f32 v[84:85], v[2:3], v[40:41] op_sel:[0,0] op_sel_hi:[1,0]
	v_pk_mul_f32 v[86:87], v[4:5], v[40:41] op_sel:[0,1] op_sel_hi:[1,1]
	v_mov_b32_dpp v24, v25 quad_perm:[0,1,2,3] row_mask:0xf bank_mask:0xa
	v_add_f32_dpp v22, v22, v22 quad_perm:[2,3,0,1] row_mask:0xf bank_mask:0xf
	v_add_f32_dpp v23, v23, v23 quad_perm:[2,3,0,1] row_mask:0xf bank_mask:0xf
	v_pk_mul_f32 v[88:89], v[6:7], v[42:43] op_sel:[0,0] op_sel_hi:[1,0]
	v_pk_mul_f32 v[90:91], v[8:9], v[42:43] op_sel:[0,1] op_sel_hi:[1,1]
	v_add_f32_dpp v24, v24, v24 row_ror:8 row_mask:0xf bank_mask:0xf
	v_add_f32_dpp v22, v22, v22 row_half_mirror row_mask:0xf bank_mask:0xf
	v_add_f32_dpp v23, v23, v23 row_half_mirror row_mask:0xf bank_mask:0xf
	v_pk_fma_f32 v[84:85], v[48:49], v[56:57], v[84:85] op_sel:[0,0,0] op_sel_hi:[0,1,1]
	v_pk_fma_f32 v[86:87], v[48:49], v[56:57], v[86:87] op_sel:[1,0,0] op_sel_hi:[1,1,1]
	v_add_f32_dpp v24, v24, v24 quad_perm:[1,0,3,2] row_mask:0xf bank_mask:0xf
	v_add_f32_dpp v22, v22, v22 row_mirror row_mask:0xf bank_mask:0xf
	v_add_f32_dpp v23, v23, v23 row_mirror row_mask:0xf bank_mask:0xf
	v_pk_fma_f32 v[88:89], v[50:51], v[56:57], v[88:89] op_sel:[0,0,0] op_sel_hi:[0,1,1]
	v_pk_fma_f32 v[90:91], v[50:51], v[56:57], v[90:91] op_sel:[1,0,0] op_sel_hi:[1,1,1]
	v_add_f32_dpp v24, v24, v24 quad_perm:[2,3,0,1] row_mask:0xf bank_mask:0xf
	v_cndmask_b32_e64 v30, v30, v24, s[16:17]
	v_pk_fma_f32 v[2:3], v[44:45], v[22:23], v[84:85] op_sel:[0,0,0] op_sel_hi:[0,1,1] neg_lo:[1,0,0] neg_hi:[1,0,0]
	v_pk_fma_f32 v[4:5], v[44:45], v[22:23], v[86:87] op_sel:[1,0,0] op_sel_hi:[1,1,1] neg_lo:[1,0,0] neg_hi:[1,0,0]
	v_pk_fma_f32 v[6:7], v[46:47], v[22:23], v[88:89] op_sel:[0,0,0] op_sel_hi:[0,1,1] neg_lo:[1,0,0] neg_hi:[1,0,0]
	v_pk_fma_f32 v[8:9], v[46:47], v[22:23], v[90:91] op_sel:[1,0,0] op_sel_hi:[1,1,1] neg_lo:[1,0,0] neg_hi:[1,0,0]
	s_waitcnt lgkmcnt(0)
	v_pk_mul_f32 v[22:23], v[2:3], v[60:61] op_sel:[0,0] op_sel_hi:[1,0]
	v_pk_mul_f32 v[24:25], v[2:3], v[52:53] op_sel:[0,0] op_sel_hi:[1,0]
	ds_read_b128 v[36:39], v20 offset:2560
	v_pk_fma_f32 v[22:23], v[4:5], v[60:61], v[22:23] op_sel:[0,1,0] op_sel_hi:[1,1,1]
	v_pk_mul_f32 v[84:85], v[4:5], v[52:53] op_sel:[0,1] op_sel_hi:[1,1]
	ds_read_b128 v[40:43], v20 offset:10752
	v_pk_fma_f32 v[22:23], v[6:7], v[62:63], v[22:23] op_sel:[0,0,0] op_sel_hi:[1,0,1]
	v_pk_fma_f32 v[24:25], v[6:7], v[54:55], v[24:25] op_sel:[0,0,0] op_sel_hi:[1,0,1]
	ds_read_b64 v[56:57], v21 offset:43520
	v_pk_fma_f32 v[22:23], v[8:9], v[62:63], v[22:23] op_sel:[0,1,0] op_sel_hi:[1,1,1]
	v_pk_fma_f32 v[84:85], v[8:9], v[54:55], v[84:85] op_sel:[0,1,0] op_sel_hi:[1,1,1]
	ds_read_b128 v[48:51], v20 offset:27136
	v_pk_add_f32 v[24:25], v[24:25], v[84:85]
	ds_read_b128 v[44:47], v20 offset:18944
	ds_read_b128 v[52:55], v20 offset:35328
	v_add_f32_dpp v26, v26, v26 row_ror:12 row_mask:0xf bank_mask:0x5
	v_add_f32_dpp v27, v27, v27 row_ror:4 row_mask:0xf bank_mask:0xa
	v_add_f32_dpp v22, v22, v22 quad_perm:[1,0,3,2] row_mask:0xf bank_mask:0xf
	v_add_f32_dpp v23, v23, v23 quad_perm:[1,0,3,2] row_mask:0xf bank_mask:0xf
	v_pk_mul_f32 v[84:85], v[2:3], v[64:65] op_sel:[0,0] op_sel_hi:[1,0]
	v_pk_mul_f32 v[86:87], v[4:5], v[64:65] op_sel:[0,1] op_sel_hi:[1,1]
	v_mov_b32_dpp v26, v27 quad_perm:[0,1,2,3] row_mask:0xf bank_mask:0xa
	v_add_f32_dpp v22, v22, v22 quad_perm:[2,3,0,1] row_mask:0xf bank_mask:0xf
	v_add_f32_dpp v23, v23, v23 quad_perm:[2,3,0,1] row_mask:0xf bank_mask:0xf
	v_pk_mul_f32 v[88:89], v[6:7], v[66:67] op_sel:[0,0] op_sel_hi:[1,0]
	v_pk_mul_f32 v[90:91], v[8:9], v[66:67] op_sel:[0,1] op_sel_hi:[1,1]
	v_add_f32_dpp v26, v26, v26 row_ror:8 row_mask:0xf bank_mask:0xf
	v_add_f32_dpp v22, v22, v22 row_half_mirror row_mask:0xf bank_mask:0xf
	v_add_f32_dpp v23, v23, v23 row_half_mirror row_mask:0xf bank_mask:0xf
	v_pk_fma_f32 v[84:85], v[72:73], v[80:81], v[84:85] op_sel:[0,0,0] op_sel_hi:[0,1,1]
	v_pk_fma_f32 v[86:87], v[72:73], v[80:81], v[86:87] op_sel:[1,0,0] op_sel_hi:[1,1,1]
	v_add_f32_dpp v26, v26, v26 quad_perm:[1,0,3,2] row_mask:0xf bank_mask:0xf
	v_add_f32_dpp v22, v22, v22 row_mirror row_mask:0xf bank_mask:0xf
	v_add_f32_dpp v23, v23, v23 row_mirror row_mask:0xf bank_mask:0xf
	v_pk_fma_f32 v[88:89], v[74:75], v[80:81], v[88:89] op_sel:[0,0,0] op_sel_hi:[0,1,1]
	v_pk_fma_f32 v[90:91], v[74:75], v[80:81], v[90:91] op_sel:[1,0,0] op_sel_hi:[1,1,1]
	v_add_f32_dpp v26, v26, v26 quad_perm:[2,3,0,1] row_mask:0xf bank_mask:0xf
	v_cndmask_b32_e32 v30, v30, v26, vcc
	v_pk_fma_f32 v[2:3], v[68:69], v[22:23], v[84:85] op_sel:[0,0,0] op_sel_hi:[0,1,1] neg_lo:[1,0,0] neg_hi:[1,0,0]
	v_pk_fma_f32 v[4:5], v[68:69], v[22:23], v[86:87] op_sel:[1,0,0] op_sel_hi:[1,1,1] neg_lo:[1,0,0] neg_hi:[1,0,0]
	v_pk_fma_f32 v[6:7], v[70:71], v[22:23], v[88:89] op_sel:[0,0,0] op_sel_hi:[0,1,1] neg_lo:[1,0,0] neg_hi:[1,0,0]
	v_pk_fma_f32 v[8:9], v[70:71], v[22:23], v[90:91] op_sel:[1,0,0] op_sel_hi:[1,1,1] neg_lo:[1,0,0] neg_hi:[1,0,0]
	s_waitcnt lgkmcnt(0)
	v_pk_mul_f32 v[22:23], v[2:3], v[36:37] op_sel:[0,0] op_sel_hi:[1,0]
	v_pk_mul_f32 v[26:27], v[2:3], v[76:77] op_sel:[0,0] op_sel_hi:[1,0]
	ds_read_b128 v[60:63], v20 offset:2816
	v_pk_fma_f32 v[22:23], v[4:5], v[36:37], v[22:23] op_sel:[0,1,0] op_sel_hi:[1,1,1]
	v_pk_mul_f32 v[84:85], v[4:5], v[76:77] op_sel:[0,1] op_sel_hi:[1,1]
	ds_read_b128 v[64:67], v20 offset:11008
	v_pk_fma_f32 v[22:23], v[6:7], v[38:39], v[22:23] op_sel:[0,0,0] op_sel_hi:[1,0,1]
	v_pk_fma_f32 v[26:27], v[6:7], v[78:79], v[26:27] op_sel:[0,0,0] op_sel_hi:[1,0,1]
	ds_read_b64 v[80:81], v21 offset:43776
	v_pk_fma_f32 v[22:23], v[8:9], v[38:39], v[22:23] op_sel:[0,1,0] op_sel_hi:[1,1,1]
	v_pk_fma_f32 v[84:85], v[8:9], v[78:79], v[84:85] op_sel:[0,1,0] op_sel_hi:[1,1,1]
	ds_read_b128 v[72:75], v20 offset:27392
	v_pk_add_f32 v[26:27], v[26:27], v[84:85]
	ds_read_b128 v[68:71], v20 offset:19200
	ds_read_b128 v[76:79], v20 offset:35584
	v_add_f32_dpp v24, v24, v24 row_ror:12 row_mask:0xf bank_mask:0x5
	v_add_f32_dpp v25, v25, v25 row_ror:4 row_mask:0xf bank_mask:0xa
	v_add_f32_dpp v22, v22, v22 quad_perm:[1,0,3,2] row_mask:0xf bank_mask:0xf
	v_add_f32_dpp v23, v23, v23 quad_perm:[1,0,3,2] row_mask:0xf bank_mask:0xf
	v_pk_mul_f32 v[84:85], v[2:3], v[40:41] op_sel:[0,0] op_sel_hi:[1,0]
	v_pk_mul_f32 v[86:87], v[4:5], v[40:41] op_sel:[0,1] op_sel_hi:[1,1]
	v_mov_b32_dpp v24, v25 quad_perm:[0,1,2,3] row_mask:0xf bank_mask:0xa
	v_add_f32_dpp v22, v22, v22 quad_perm:[2,3,0,1] row_mask:0xf bank_mask:0xf
	v_add_f32_dpp v23, v23, v23 quad_perm:[2,3,0,1] row_mask:0xf bank_mask:0xf
	v_pk_mul_f32 v[88:89], v[6:7], v[42:43] op_sel:[0,0] op_sel_hi:[1,0]
	v_pk_mul_f32 v[90:91], v[8:9], v[42:43] op_sel:[0,1] op_sel_hi:[1,1]
	v_add_f32_dpp v24, v24, v24 row_ror:8 row_mask:0xf bank_mask:0xf
	v_add_f32_dpp v22, v22, v22 row_half_mirror row_mask:0xf bank_mask:0xf
	v_add_f32_dpp v23, v23, v23 row_half_mirror row_mask:0xf bank_mask:0xf
	v_pk_fma_f32 v[84:85], v[48:49], v[56:57], v[84:85] op_sel:[0,0,0] op_sel_hi:[0,1,1]
	v_pk_fma_f32 v[86:87], v[48:49], v[56:57], v[86:87] op_sel:[1,0,0] op_sel_hi:[1,1,1]
	v_add_f32_dpp v24, v24, v24 quad_perm:[1,0,3,2] row_mask:0xf bank_mask:0xf
	v_add_f32_dpp v22, v22, v22 row_mirror row_mask:0xf bank_mask:0xf
	v_add_f32_dpp v23, v23, v23 row_mirror row_mask:0xf bank_mask:0xf
	v_pk_fma_f32 v[88:89], v[50:51], v[56:57], v[88:89] op_sel:[0,0,0] op_sel_hi:[0,1,1]
	v_pk_fma_f32 v[90:91], v[50:51], v[56:57], v[90:91] op_sel:[1,0,0] op_sel_hi:[1,1,1]
	v_add_f32_dpp v24, v24, v24 quad_perm:[2,3,0,1] row_mask:0xf bank_mask:0xf
	v_cndmask_b32_e64 v31, 0, v24, s[0:1]
	v_pk_fma_f32 v[2:3], v[44:45], v[22:23], v[84:85] op_sel:[0,0,0] op_sel_hi:[0,1,1] neg_lo:[1,0,0] neg_hi:[1,0,0]
	v_pk_fma_f32 v[4:5], v[44:45], v[22:23], v[86:87] op_sel:[1,0,0] op_sel_hi:[1,1,1] neg_lo:[1,0,0] neg_hi:[1,0,0]
	v_pk_fma_f32 v[6:7], v[46:47], v[22:23], v[88:89] op_sel:[0,0,0] op_sel_hi:[0,1,1] neg_lo:[1,0,0] neg_hi:[1,0,0]
	v_pk_fma_f32 v[8:9], v[46:47], v[22:23], v[90:91] op_sel:[1,0,0] op_sel_hi:[1,1,1] neg_lo:[1,0,0] neg_hi:[1,0,0]
	s_waitcnt lgkmcnt(0)
	v_pk_mul_f32 v[22:23], v[2:3], v[60:61] op_sel:[0,0] op_sel_hi:[1,0]
	v_pk_mul_f32 v[24:25], v[2:3], v[52:53] op_sel:[0,0] op_sel_hi:[1,0]
	ds_read_b128 v[36:39], v20 offset:3072
	v_pk_fma_f32 v[22:23], v[4:5], v[60:61], v[22:23] op_sel:[0,1,0] op_sel_hi:[1,1,1]
	v_pk_mul_f32 v[84:85], v[4:5], v[52:53] op_sel:[0,1] op_sel_hi:[1,1]
	ds_read_b128 v[40:43], v20 offset:11264
	v_pk_fma_f32 v[22:23], v[6:7], v[62:63], v[22:23] op_sel:[0,0,0] op_sel_hi:[1,0,1]
	v_pk_fma_f32 v[24:25], v[6:7], v[54:55], v[24:25] op_sel:[0,0,0] op_sel_hi:[1,0,1]
	ds_read_b64 v[56:57], v21 offset:44032
	v_pk_fma_f32 v[22:23], v[8:9], v[62:63], v[22:23] op_sel:[0,1,0] op_sel_hi:[1,1,1]
	v_pk_fma_f32 v[84:85], v[8:9], v[54:55], v[84:85] op_sel:[0,1,0] op_sel_hi:[1,1,1]
	ds_read_b128 v[48:51], v20 offset:27648
	v_pk_add_f32 v[24:25], v[24:25], v[84:85]
	ds_read_b128 v[44:47], v20 offset:19456
	ds_read_b128 v[52:55], v20 offset:35840
	v_add_f32_dpp v26, v26, v26 row_ror:12 row_mask:0xf bank_mask:0x5
	v_add_f32_dpp v27, v27, v27 row_ror:4 row_mask:0xf bank_mask:0xa
	v_add_f32_dpp v22, v22, v22 quad_perm:[1,0,3,2] row_mask:0xf bank_mask:0xf
	v_add_f32_dpp v23, v23, v23 quad_perm:[1,0,3,2] row_mask:0xf bank_mask:0xf
	v_pk_mul_f32 v[84:85], v[2:3], v[64:65] op_sel:[0,0] op_sel_hi:[1,0]
	v_pk_mul_f32 v[86:87], v[4:5], v[64:65] op_sel:[0,1] op_sel_hi:[1,1]
	v_mov_b32_dpp v26, v27 quad_perm:[0,1,2,3] row_mask:0xf bank_mask:0xa
	v_add_f32_dpp v22, v22, v22 quad_perm:[2,3,0,1] row_mask:0xf bank_mask:0xf
	v_add_f32_dpp v23, v23, v23 quad_perm:[2,3,0,1] row_mask:0xf bank_mask:0xf
	v_pk_mul_f32 v[88:89], v[6:7], v[66:67] op_sel:[0,0] op_sel_hi:[1,0]
	v_pk_mul_f32 v[90:91], v[8:9], v[66:67] op_sel:[0,1] op_sel_hi:[1,1]
	v_add_f32_dpp v26, v26, v26 row_ror:8 row_mask:0xf bank_mask:0xf
	v_add_f32_dpp v22, v22, v22 row_half_mirror row_mask:0xf bank_mask:0xf
	v_add_f32_dpp v23, v23, v23 row_half_mirror row_mask:0xf bank_mask:0xf
	v_pk_fma_f32 v[84:85], v[72:73], v[80:81], v[84:85] op_sel:[0,0,0] op_sel_hi:[0,1,1]
	v_pk_fma_f32 v[86:87], v[72:73], v[80:81], v[86:87] op_sel:[1,0,0] op_sel_hi:[1,1,1]
	v_add_f32_dpp v26, v26, v26 quad_perm:[1,0,3,2] row_mask:0xf bank_mask:0xf
	v_add_f32_dpp v22, v22, v22 row_mirror row_mask:0xf bank_mask:0xf
	v_add_f32_dpp v23, v23, v23 row_mirror row_mask:0xf bank_mask:0xf
	v_pk_fma_f32 v[88:89], v[74:75], v[80:81], v[88:89] op_sel:[0,0,0] op_sel_hi:[0,1,1]
	v_pk_fma_f32 v[90:91], v[74:75], v[80:81], v[90:91] op_sel:[1,0,0] op_sel_hi:[1,1,1]
	v_add_f32_dpp v26, v26, v26 quad_perm:[2,3,0,1] row_mask:0xf bank_mask:0xf
	v_cndmask_b32_e64 v31, v31, v26, s[6:7]
	v_pk_fma_f32 v[2:3], v[68:69], v[22:23], v[84:85] op_sel:[0,0,0] op_sel_hi:[0,1,1] neg_lo:[1,0,0] neg_hi:[1,0,0]
	v_pk_fma_f32 v[4:5], v[68:69], v[22:23], v[86:87] op_sel:[1,0,0] op_sel_hi:[1,1,1] neg_lo:[1,0,0] neg_hi:[1,0,0]
	v_pk_fma_f32 v[6:7], v[70:71], v[22:23], v[88:89] op_sel:[0,0,0] op_sel_hi:[0,1,1] neg_lo:[1,0,0] neg_hi:[1,0,0]
	v_pk_fma_f32 v[8:9], v[70:71], v[22:23], v[90:91] op_sel:[1,0,0] op_sel_hi:[1,1,1] neg_lo:[1,0,0] neg_hi:[1,0,0]
	s_waitcnt lgkmcnt(0)
	v_pk_mul_f32 v[22:23], v[2:3], v[36:37] op_sel:[0,0] op_sel_hi:[1,0]
	v_pk_mul_f32 v[26:27], v[2:3], v[76:77] op_sel:[0,0] op_sel_hi:[1,0]
	ds_read_b128 v[60:63], v20 offset:3328
	v_pk_fma_f32 v[22:23], v[4:5], v[36:37], v[22:23] op_sel:[0,1,0] op_sel_hi:[1,1,1]
	v_pk_mul_f32 v[84:85], v[4:5], v[76:77] op_sel:[0,1] op_sel_hi:[1,1]
	ds_read_b128 v[64:67], v20 offset:11520
	v_pk_fma_f32 v[22:23], v[6:7], v[38:39], v[22:23] op_sel:[0,0,0] op_sel_hi:[1,0,1]
	v_pk_fma_f32 v[26:27], v[6:7], v[78:79], v[26:27] op_sel:[0,0,0] op_sel_hi:[1,0,1]
	ds_read_b64 v[80:81], v21 offset:44288
	v_pk_fma_f32 v[22:23], v[8:9], v[38:39], v[22:23] op_sel:[0,1,0] op_sel_hi:[1,1,1]
	v_pk_fma_f32 v[84:85], v[8:9], v[78:79], v[84:85] op_sel:[0,1,0] op_sel_hi:[1,1,1]
	ds_read_b128 v[72:75], v20 offset:27904
	v_pk_add_f32 v[26:27], v[26:27], v[84:85]
	ds_read_b128 v[68:71], v20 offset:19712
	ds_read_b128 v[76:79], v20 offset:36096
	v_add_f32_dpp v24, v24, v24 row_ror:12 row_mask:0xf bank_mask:0x5
	v_add_f32_dpp v25, v25, v25 row_ror:4 row_mask:0xf bank_mask:0xa
	v_add_f32_dpp v22, v22, v22 quad_perm:[1,0,3,2] row_mask:0xf bank_mask:0xf
	v_add_f32_dpp v23, v23, v23 quad_perm:[1,0,3,2] row_mask:0xf bank_mask:0xf
	v_pk_mul_f32 v[84:85], v[2:3], v[40:41] op_sel:[0,0] op_sel_hi:[1,0]
	v_pk_mul_f32 v[86:87], v[4:5], v[40:41] op_sel:[0,1] op_sel_hi:[1,1]
	v_mov_b32_dpp v24, v25 quad_perm:[0,1,2,3] row_mask:0xf bank_mask:0xa
	v_add_f32_dpp v22, v22, v22 quad_perm:[2,3,0,1] row_mask:0xf bank_mask:0xf
	v_add_f32_dpp v23, v23, v23 quad_perm:[2,3,0,1] row_mask:0xf bank_mask:0xf
	v_pk_mul_f32 v[88:89], v[6:7], v[42:43] op_sel:[0,0] op_sel_hi:[1,0]
	v_pk_mul_f32 v[90:91], v[8:9], v[42:43] op_sel:[0,1] op_sel_hi:[1,1]
	v_add_f32_dpp v24, v24, v24 row_ror:8 row_mask:0xf bank_mask:0xf
	v_add_f32_dpp v22, v22, v22 row_half_mirror row_mask:0xf bank_mask:0xf
	v_add_f32_dpp v23, v23, v23 row_half_mirror row_mask:0xf bank_mask:0xf
	v_pk_fma_f32 v[84:85], v[48:49], v[56:57], v[84:85] op_sel:[0,0,0] op_sel_hi:[0,1,1]
	v_pk_fma_f32 v[86:87], v[48:49], v[56:57], v[86:87] op_sel:[1,0,0] op_sel_hi:[1,1,1]
	v_add_f32_dpp v24, v24, v24 quad_perm:[1,0,3,2] row_mask:0xf bank_mask:0xf
	v_add_f32_dpp v22, v22, v22 row_mirror row_mask:0xf bank_mask:0xf
	v_add_f32_dpp v23, v23, v23 row_mirror row_mask:0xf bank_mask:0xf
	v_pk_fma_f32 v[88:89], v[50:51], v[56:57], v[88:89] op_sel:[0,0,0] op_sel_hi:[0,1,1]
	v_pk_fma_f32 v[90:91], v[50:51], v[56:57], v[90:91] op_sel:[1,0,0] op_sel_hi:[1,1,1]
	v_add_f32_dpp v24, v24, v24 quad_perm:[2,3,0,1] row_mask:0xf bank_mask:0xf
	v_cndmask_b32_e64 v31, v31, v24, s[8:9]
	v_pk_fma_f32 v[2:3], v[44:45], v[22:23], v[84:85] op_sel:[0,0,0] op_sel_hi:[0,1,1] neg_lo:[1,0,0] neg_hi:[1,0,0]
	v_pk_fma_f32 v[4:5], v[44:45], v[22:23], v[86:87] op_sel:[1,0,0] op_sel_hi:[1,1,1] neg_lo:[1,0,0] neg_hi:[1,0,0]
	v_pk_fma_f32 v[6:7], v[46:47], v[22:23], v[88:89] op_sel:[0,0,0] op_sel_hi:[0,1,1] neg_lo:[1,0,0] neg_hi:[1,0,0]
	v_pk_fma_f32 v[8:9], v[46:47], v[22:23], v[90:91] op_sel:[1,0,0] op_sel_hi:[1,1,1] neg_lo:[1,0,0] neg_hi:[1,0,0]
	s_waitcnt lgkmcnt(0)
	v_pk_mul_f32 v[22:23], v[2:3], v[60:61] op_sel:[0,0] op_sel_hi:[1,0]
	v_pk_mul_f32 v[24:25], v[2:3], v[52:53] op_sel:[0,0] op_sel_hi:[1,0]
	ds_read_b128 v[36:39], v20 offset:3584
	v_pk_fma_f32 v[22:23], v[4:5], v[60:61], v[22:23] op_sel:[0,1,0] op_sel_hi:[1,1,1]
	v_pk_mul_f32 v[84:85], v[4:5], v[52:53] op_sel:[0,1] op_sel_hi:[1,1]
	ds_read_b128 v[40:43], v20 offset:11776
	v_pk_fma_f32 v[22:23], v[6:7], v[62:63], v[22:23] op_sel:[0,0,0] op_sel_hi:[1,0,1]
	v_pk_fma_f32 v[24:25], v[6:7], v[54:55], v[24:25] op_sel:[0,0,0] op_sel_hi:[1,0,1]
	ds_read_b64 v[56:57], v21 offset:44544
	v_pk_fma_f32 v[22:23], v[8:9], v[62:63], v[22:23] op_sel:[0,1,0] op_sel_hi:[1,1,1]
	v_pk_fma_f32 v[84:85], v[8:9], v[54:55], v[84:85] op_sel:[0,1,0] op_sel_hi:[1,1,1]
	ds_read_b128 v[48:51], v20 offset:28160
	v_pk_add_f32 v[24:25], v[24:25], v[84:85]
	ds_read_b128 v[44:47], v20 offset:19968
	ds_read_b128 v[52:55], v20 offset:36352
	v_add_f32_dpp v26, v26, v26 row_ror:12 row_mask:0xf bank_mask:0x5
	v_add_f32_dpp v27, v27, v27 row_ror:4 row_mask:0xf bank_mask:0xa
	v_add_f32_dpp v22, v22, v22 quad_perm:[1,0,3,2] row_mask:0xf bank_mask:0xf
	v_add_f32_dpp v23, v23, v23 quad_perm:[1,0,3,2] row_mask:0xf bank_mask:0xf
	v_pk_mul_f32 v[84:85], v[2:3], v[64:65] op_sel:[0,0] op_sel_hi:[1,0]
	v_pk_mul_f32 v[86:87], v[4:5], v[64:65] op_sel:[0,1] op_sel_hi:[1,1]
	v_mov_b32_dpp v26, v27 quad_perm:[0,1,2,3] row_mask:0xf bank_mask:0xa
	v_add_f32_dpp v22, v22, v22 quad_perm:[2,3,0,1] row_mask:0xf bank_mask:0xf
	v_add_f32_dpp v23, v23, v23 quad_perm:[2,3,0,1] row_mask:0xf bank_mask:0xf
	v_pk_mul_f32 v[88:89], v[6:7], v[66:67] op_sel:[0,0] op_sel_hi:[1,0]
	v_pk_mul_f32 v[90:91], v[8:9], v[66:67] op_sel:[0,1] op_sel_hi:[1,1]
	v_add_f32_dpp v26, v26, v26 row_ror:8 row_mask:0xf bank_mask:0xf
	v_add_f32_dpp v22, v22, v22 row_half_mirror row_mask:0xf bank_mask:0xf
	v_add_f32_dpp v23, v23, v23 row_half_mirror row_mask:0xf bank_mask:0xf
	v_pk_fma_f32 v[84:85], v[72:73], v[80:81], v[84:85] op_sel:[0,0,0] op_sel_hi:[0,1,1]
	v_pk_fma_f32 v[86:87], v[72:73], v[80:81], v[86:87] op_sel:[1,0,0] op_sel_hi:[1,1,1]
	v_add_f32_dpp v26, v26, v26 quad_perm:[1,0,3,2] row_mask:0xf bank_mask:0xf
	v_add_f32_dpp v22, v22, v22 row_mirror row_mask:0xf bank_mask:0xf
	v_add_f32_dpp v23, v23, v23 row_mirror row_mask:0xf bank_mask:0xf
	v_pk_fma_f32 v[88:89], v[74:75], v[80:81], v[88:89] op_sel:[0,0,0] op_sel_hi:[0,1,1]
	v_pk_fma_f32 v[90:91], v[74:75], v[80:81], v[90:91] op_sel:[1,0,0] op_sel_hi:[1,1,1]
	v_add_f32_dpp v26, v26, v26 quad_perm:[2,3,0,1] row_mask:0xf bank_mask:0xf
	v_cndmask_b32_e64 v31, v31, v26, s[10:11]
	v_pk_fma_f32 v[2:3], v[68:69], v[22:23], v[84:85] op_sel:[0,0,0] op_sel_hi:[0,1,1] neg_lo:[1,0,0] neg_hi:[1,0,0]
	v_pk_fma_f32 v[4:5], v[68:69], v[22:23], v[86:87] op_sel:[1,0,0] op_sel_hi:[1,1,1] neg_lo:[1,0,0] neg_hi:[1,0,0]
	v_pk_fma_f32 v[6:7], v[70:71], v[22:23], v[88:89] op_sel:[0,0,0] op_sel_hi:[0,1,1] neg_lo:[1,0,0] neg_hi:[1,0,0]
	v_pk_fma_f32 v[8:9], v[70:71], v[22:23], v[90:91] op_sel:[1,0,0] op_sel_hi:[1,1,1] neg_lo:[1,0,0] neg_hi:[1,0,0]
	s_waitcnt lgkmcnt(0)
	v_pk_mul_f32 v[22:23], v[2:3], v[36:37] op_sel:[0,0] op_sel_hi:[1,0]
	v_pk_mul_f32 v[26:27], v[2:3], v[76:77] op_sel:[0,0] op_sel_hi:[1,0]
	ds_read_b128 v[60:63], v20 offset:3840
	v_pk_fma_f32 v[22:23], v[4:5], v[36:37], v[22:23] op_sel:[0,1,0] op_sel_hi:[1,1,1]
	v_pk_mul_f32 v[84:85], v[4:5], v[76:77] op_sel:[0,1] op_sel_hi:[1,1]
	ds_read_b128 v[64:67], v20 offset:12032
	v_pk_fma_f32 v[22:23], v[6:7], v[38:39], v[22:23] op_sel:[0,0,0] op_sel_hi:[1,0,1]
	v_pk_fma_f32 v[26:27], v[6:7], v[78:79], v[26:27] op_sel:[0,0,0] op_sel_hi:[1,0,1]
	ds_read_b64 v[80:81], v21 offset:44800
	v_pk_fma_f32 v[22:23], v[8:9], v[38:39], v[22:23] op_sel:[0,1,0] op_sel_hi:[1,1,1]
	v_pk_fma_f32 v[84:85], v[8:9], v[78:79], v[84:85] op_sel:[0,1,0] op_sel_hi:[1,1,1]
	ds_read_b128 v[72:75], v20 offset:28416
	v_pk_add_f32 v[26:27], v[26:27], v[84:85]
	ds_read_b128 v[68:71], v20 offset:20224
	ds_read_b128 v[76:79], v20 offset:36608
	v_add_f32_dpp v24, v24, v24 row_ror:12 row_mask:0xf bank_mask:0x5
	v_add_f32_dpp v25, v25, v25 row_ror:4 row_mask:0xf bank_mask:0xa
	v_add_f32_dpp v22, v22, v22 quad_perm:[1,0,3,2] row_mask:0xf bank_mask:0xf
	v_add_f32_dpp v23, v23, v23 quad_perm:[1,0,3,2] row_mask:0xf bank_mask:0xf
	v_pk_mul_f32 v[84:85], v[2:3], v[40:41] op_sel:[0,0] op_sel_hi:[1,0]
	v_pk_mul_f32 v[86:87], v[4:5], v[40:41] op_sel:[0,1] op_sel_hi:[1,1]
	v_mov_b32_dpp v24, v25 quad_perm:[0,1,2,3] row_mask:0xf bank_mask:0xa
	v_add_f32_dpp v22, v22, v22 quad_perm:[2,3,0,1] row_mask:0xf bank_mask:0xf
	v_add_f32_dpp v23, v23, v23 quad_perm:[2,3,0,1] row_mask:0xf bank_mask:0xf
	v_pk_mul_f32 v[88:89], v[6:7], v[42:43] op_sel:[0,0] op_sel_hi:[1,0]
	v_pk_mul_f32 v[90:91], v[8:9], v[42:43] op_sel:[0,1] op_sel_hi:[1,1]
	v_add_f32_dpp v24, v24, v24 row_ror:8 row_mask:0xf bank_mask:0xf
	v_add_f32_dpp v22, v22, v22 row_half_mirror row_mask:0xf bank_mask:0xf
	v_add_f32_dpp v23, v23, v23 row_half_mirror row_mask:0xf bank_mask:0xf
	v_pk_fma_f32 v[84:85], v[48:49], v[56:57], v[84:85] op_sel:[0,0,0] op_sel_hi:[0,1,1]
	v_pk_fma_f32 v[86:87], v[48:49], v[56:57], v[86:87] op_sel:[1,0,0] op_sel_hi:[1,1,1]
	v_add_f32_dpp v24, v24, v24 quad_perm:[1,0,3,2] row_mask:0xf bank_mask:0xf
	v_add_f32_dpp v22, v22, v22 row_mirror row_mask:0xf bank_mask:0xf
	v_add_f32_dpp v23, v23, v23 row_mirror row_mask:0xf bank_mask:0xf
	v_pk_fma_f32 v[88:89], v[50:51], v[56:57], v[88:89] op_sel:[0,0,0] op_sel_hi:[0,1,1]
	v_pk_fma_f32 v[90:91], v[50:51], v[56:57], v[90:91] op_sel:[1,0,0] op_sel_hi:[1,1,1]
	v_add_f32_dpp v24, v24, v24 quad_perm:[2,3,0,1] row_mask:0xf bank_mask:0xf
	v_cndmask_b32_e64 v31, v31, v24, s[12:13]
	v_pk_fma_f32 v[2:3], v[44:45], v[22:23], v[84:85] op_sel:[0,0,0] op_sel_hi:[0,1,1] neg_lo:[1,0,0] neg_hi:[1,0,0]
	v_pk_fma_f32 v[4:5], v[44:45], v[22:23], v[86:87] op_sel:[1,0,0] op_sel_hi:[1,1,1] neg_lo:[1,0,0] neg_hi:[1,0,0]
	v_pk_fma_f32 v[6:7], v[46:47], v[22:23], v[88:89] op_sel:[0,0,0] op_sel_hi:[0,1,1] neg_lo:[1,0,0] neg_hi:[1,0,0]
	v_pk_fma_f32 v[8:9], v[46:47], v[22:23], v[90:91] op_sel:[1,0,0] op_sel_hi:[1,1,1] neg_lo:[1,0,0] neg_hi:[1,0,0]
	s_waitcnt lgkmcnt(0)
	v_pk_mul_f32 v[22:23], v[2:3], v[60:61] op_sel:[0,0] op_sel_hi:[1,0]
	v_pk_mul_f32 v[24:25], v[2:3], v[52:53] op_sel:[0,0] op_sel_hi:[1,0]
	ds_read_b128 v[36:39], v20 offset:4096
	v_pk_fma_f32 v[22:23], v[4:5], v[60:61], v[22:23] op_sel:[0,1,0] op_sel_hi:[1,1,1]
	v_pk_mul_f32 v[84:85], v[4:5], v[52:53] op_sel:[0,1] op_sel_hi:[1,1]
	ds_read_b128 v[40:43], v20 offset:12288
	v_pk_fma_f32 v[22:23], v[6:7], v[62:63], v[22:23] op_sel:[0,0,0] op_sel_hi:[1,0,1]
	v_pk_fma_f32 v[24:25], v[6:7], v[54:55], v[24:25] op_sel:[0,0,0] op_sel_hi:[1,0,1]
	ds_read_b64 v[56:57], v21 offset:45056
	v_pk_fma_f32 v[22:23], v[8:9], v[62:63], v[22:23] op_sel:[0,1,0] op_sel_hi:[1,1,1]
	v_pk_fma_f32 v[84:85], v[8:9], v[54:55], v[84:85] op_sel:[0,1,0] op_sel_hi:[1,1,1]
	ds_read_b128 v[48:51], v20 offset:28672
	v_pk_add_f32 v[24:25], v[24:25], v[84:85]
	ds_read_b128 v[44:47], v20 offset:20480
	ds_read_b128 v[52:55], v20 offset:36864
	v_add_f32_dpp v26, v26, v26 row_ror:12 row_mask:0xf bank_mask:0x5
	v_add_f32_dpp v27, v27, v27 row_ror:4 row_mask:0xf bank_mask:0xa
	v_add_f32_dpp v22, v22, v22 quad_perm:[1,0,3,2] row_mask:0xf bank_mask:0xf
	v_add_f32_dpp v23, v23, v23 quad_perm:[1,0,3,2] row_mask:0xf bank_mask:0xf
	v_pk_mul_f32 v[84:85], v[2:3], v[64:65] op_sel:[0,0] op_sel_hi:[1,0]
	v_pk_mul_f32 v[86:87], v[4:5], v[64:65] op_sel:[0,1] op_sel_hi:[1,1]
	v_mov_b32_dpp v26, v27 quad_perm:[0,1,2,3] row_mask:0xf bank_mask:0xa
	v_add_f32_dpp v22, v22, v22 quad_perm:[2,3,0,1] row_mask:0xf bank_mask:0xf
	v_add_f32_dpp v23, v23, v23 quad_perm:[2,3,0,1] row_mask:0xf bank_mask:0xf
	v_pk_mul_f32 v[88:89], v[6:7], v[66:67] op_sel:[0,0] op_sel_hi:[1,0]
	v_pk_mul_f32 v[90:91], v[8:9], v[66:67] op_sel:[0,1] op_sel_hi:[1,1]
	v_add_f32_dpp v26, v26, v26 row_ror:8 row_mask:0xf bank_mask:0xf
	v_add_f32_dpp v22, v22, v22 row_half_mirror row_mask:0xf bank_mask:0xf
	v_add_f32_dpp v23, v23, v23 row_half_mirror row_mask:0xf bank_mask:0xf
	v_pk_fma_f32 v[84:85], v[72:73], v[80:81], v[84:85] op_sel:[0,0,0] op_sel_hi:[0,1,1]
	v_pk_fma_f32 v[86:87], v[72:73], v[80:81], v[86:87] op_sel:[1,0,0] op_sel_hi:[1,1,1]
	v_add_f32_dpp v26, v26, v26 quad_perm:[1,0,3,2] row_mask:0xf bank_mask:0xf
	v_add_f32_dpp v22, v22, v22 row_mirror row_mask:0xf bank_mask:0xf
	v_add_f32_dpp v23, v23, v23 row_mirror row_mask:0xf bank_mask:0xf
	v_pk_fma_f32 v[88:89], v[74:75], v[80:81], v[88:89] op_sel:[0,0,0] op_sel_hi:[0,1,1]
	v_pk_fma_f32 v[90:91], v[74:75], v[80:81], v[90:91] op_sel:[1,0,0] op_sel_hi:[1,1,1]
	v_add_f32_dpp v26, v26, v26 quad_perm:[2,3,0,1] row_mask:0xf bank_mask:0xf
	v_cndmask_b32_e64 v31, v31, v26, s[14:15]
	v_pk_fma_f32 v[2:3], v[68:69], v[22:23], v[84:85] op_sel:[0,0,0] op_sel_hi:[0,1,1] neg_lo:[1,0,0] neg_hi:[1,0,0]
	v_pk_fma_f32 v[4:5], v[68:69], v[22:23], v[86:87] op_sel:[1,0,0] op_sel_hi:[1,1,1] neg_lo:[1,0,0] neg_hi:[1,0,0]
	v_pk_fma_f32 v[6:7], v[70:71], v[22:23], v[88:89] op_sel:[0,0,0] op_sel_hi:[0,1,1] neg_lo:[1,0,0] neg_hi:[1,0,0]
	v_pk_fma_f32 v[8:9], v[70:71], v[22:23], v[90:91] op_sel:[1,0,0] op_sel_hi:[1,1,1] neg_lo:[1,0,0] neg_hi:[1,0,0]
	s_waitcnt lgkmcnt(0)
	v_pk_mul_f32 v[22:23], v[2:3], v[36:37] op_sel:[0,0] op_sel_hi:[1,0]
	v_pk_mul_f32 v[26:27], v[2:3], v[76:77] op_sel:[0,0] op_sel_hi:[1,0]
	ds_read_b128 v[60:63], v20 offset:4352
	v_pk_fma_f32 v[22:23], v[4:5], v[36:37], v[22:23] op_sel:[0,1,0] op_sel_hi:[1,1,1]
	v_pk_mul_f32 v[84:85], v[4:5], v[76:77] op_sel:[0,1] op_sel_hi:[1,1]
	ds_read_b128 v[64:67], v20 offset:12544
	v_pk_fma_f32 v[22:23], v[6:7], v[38:39], v[22:23] op_sel:[0,0,0] op_sel_hi:[1,0,1]
	v_pk_fma_f32 v[26:27], v[6:7], v[78:79], v[26:27] op_sel:[0,0,0] op_sel_hi:[1,0,1]
	ds_read_b64 v[80:81], v21 offset:45312
	v_pk_fma_f32 v[22:23], v[8:9], v[38:39], v[22:23] op_sel:[0,1,0] op_sel_hi:[1,1,1]
	v_pk_fma_f32 v[84:85], v[8:9], v[78:79], v[84:85] op_sel:[0,1,0] op_sel_hi:[1,1,1]
	ds_read_b128 v[72:75], v20 offset:28928
	v_pk_add_f32 v[26:27], v[26:27], v[84:85]
	ds_read_b128 v[68:71], v20 offset:20736
	ds_read_b128 v[76:79], v20 offset:37120
	v_add_f32_dpp v24, v24, v24 row_ror:12 row_mask:0xf bank_mask:0x5
	v_add_f32_dpp v25, v25, v25 row_ror:4 row_mask:0xf bank_mask:0xa
	v_add_f32_dpp v22, v22, v22 quad_perm:[1,0,3,2] row_mask:0xf bank_mask:0xf
	v_add_f32_dpp v23, v23, v23 quad_perm:[1,0,3,2] row_mask:0xf bank_mask:0xf
	v_pk_mul_f32 v[84:85], v[2:3], v[40:41] op_sel:[0,0] op_sel_hi:[1,0]
	v_pk_mul_f32 v[86:87], v[4:5], v[40:41] op_sel:[0,1] op_sel_hi:[1,1]
	v_mov_b32_dpp v24, v25 quad_perm:[0,1,2,3] row_mask:0xf bank_mask:0xa
	v_add_f32_dpp v22, v22, v22 quad_perm:[2,3,0,1] row_mask:0xf bank_mask:0xf
	v_add_f32_dpp v23, v23, v23 quad_perm:[2,3,0,1] row_mask:0xf bank_mask:0xf
	v_pk_mul_f32 v[88:89], v[6:7], v[42:43] op_sel:[0,0] op_sel_hi:[1,0]
	v_pk_mul_f32 v[90:91], v[8:9], v[42:43] op_sel:[0,1] op_sel_hi:[1,1]
	v_add_f32_dpp v24, v24, v24 row_ror:8 row_mask:0xf bank_mask:0xf
	v_add_f32_dpp v22, v22, v22 row_half_mirror row_mask:0xf bank_mask:0xf
	v_add_f32_dpp v23, v23, v23 row_half_mirror row_mask:0xf bank_mask:0xf
	v_pk_fma_f32 v[84:85], v[48:49], v[56:57], v[84:85] op_sel:[0,0,0] op_sel_hi:[0,1,1]
	v_pk_fma_f32 v[86:87], v[48:49], v[56:57], v[86:87] op_sel:[1,0,0] op_sel_hi:[1,1,1]
	v_add_f32_dpp v24, v24, v24 quad_perm:[1,0,3,2] row_mask:0xf bank_mask:0xf
	v_add_f32_dpp v22, v22, v22 row_mirror row_mask:0xf bank_mask:0xf
	v_add_f32_dpp v23, v23, v23 row_mirror row_mask:0xf bank_mask:0xf
	v_pk_fma_f32 v[88:89], v[50:51], v[56:57], v[88:89] op_sel:[0,0,0] op_sel_hi:[0,1,1]
	v_pk_fma_f32 v[90:91], v[50:51], v[56:57], v[90:91] op_sel:[1,0,0] op_sel_hi:[1,1,1]
	v_add_f32_dpp v24, v24, v24 quad_perm:[2,3,0,1] row_mask:0xf bank_mask:0xf
	v_cndmask_b32_e64 v31, v31, v24, s[16:17]
	v_pk_fma_f32 v[2:3], v[44:45], v[22:23], v[84:85] op_sel:[0,0,0] op_sel_hi:[0,1,1] neg_lo:[1,0,0] neg_hi:[1,0,0]
	v_pk_fma_f32 v[4:5], v[44:45], v[22:23], v[86:87] op_sel:[1,0,0] op_sel_hi:[1,1,1] neg_lo:[1,0,0] neg_hi:[1,0,0]
	v_pk_fma_f32 v[6:7], v[46:47], v[22:23], v[88:89] op_sel:[0,0,0] op_sel_hi:[0,1,1] neg_lo:[1,0,0] neg_hi:[1,0,0]
	v_pk_fma_f32 v[8:9], v[46:47], v[22:23], v[90:91] op_sel:[1,0,0] op_sel_hi:[1,1,1] neg_lo:[1,0,0] neg_hi:[1,0,0]
	s_waitcnt lgkmcnt(0)
	v_pk_mul_f32 v[22:23], v[2:3], v[60:61] op_sel:[0,0] op_sel_hi:[1,0]
	v_pk_mul_f32 v[24:25], v[2:3], v[52:53] op_sel:[0,0] op_sel_hi:[1,0]
	ds_read_b128 v[36:39], v20 offset:4608
	v_pk_fma_f32 v[22:23], v[4:5], v[60:61], v[22:23] op_sel:[0,1,0] op_sel_hi:[1,1,1]
	v_pk_mul_f32 v[84:85], v[4:5], v[52:53] op_sel:[0,1] op_sel_hi:[1,1]
	ds_read_b128 v[40:43], v20 offset:12800
	v_pk_fma_f32 v[22:23], v[6:7], v[62:63], v[22:23] op_sel:[0,0,0] op_sel_hi:[1,0,1]
	v_pk_fma_f32 v[24:25], v[6:7], v[54:55], v[24:25] op_sel:[0,0,0] op_sel_hi:[1,0,1]
	ds_read_b64 v[56:57], v21 offset:45568
	v_pk_fma_f32 v[22:23], v[8:9], v[62:63], v[22:23] op_sel:[0,1,0] op_sel_hi:[1,1,1]
	v_pk_fma_f32 v[84:85], v[8:9], v[54:55], v[84:85] op_sel:[0,1,0] op_sel_hi:[1,1,1]
	ds_read_b128 v[48:51], v20 offset:29184
	v_pk_add_f32 v[24:25], v[24:25], v[84:85]
	ds_read_b128 v[44:47], v20 offset:20992
	ds_read_b128 v[52:55], v20 offset:37376
	v_add_f32_dpp v26, v26, v26 row_ror:12 row_mask:0xf bank_mask:0x5
	v_add_f32_dpp v27, v27, v27 row_ror:4 row_mask:0xf bank_mask:0xa
	v_add_f32_dpp v22, v22, v22 quad_perm:[1,0,3,2] row_mask:0xf bank_mask:0xf
	v_add_f32_dpp v23, v23, v23 quad_perm:[1,0,3,2] row_mask:0xf bank_mask:0xf
	v_pk_mul_f32 v[84:85], v[2:3], v[64:65] op_sel:[0,0] op_sel_hi:[1,0]
	v_pk_mul_f32 v[86:87], v[4:5], v[64:65] op_sel:[0,1] op_sel_hi:[1,1]
	v_mov_b32_dpp v26, v27 quad_perm:[0,1,2,3] row_mask:0xf bank_mask:0xa
	v_add_f32_dpp v22, v22, v22 quad_perm:[2,3,0,1] row_mask:0xf bank_mask:0xf
	v_add_f32_dpp v23, v23, v23 quad_perm:[2,3,0,1] row_mask:0xf bank_mask:0xf
	v_pk_mul_f32 v[88:89], v[6:7], v[66:67] op_sel:[0,0] op_sel_hi:[1,0]
	v_pk_mul_f32 v[90:91], v[8:9], v[66:67] op_sel:[0,1] op_sel_hi:[1,1]
	v_add_f32_dpp v26, v26, v26 row_ror:8 row_mask:0xf bank_mask:0xf
	v_add_f32_dpp v22, v22, v22 row_half_mirror row_mask:0xf bank_mask:0xf
	v_add_f32_dpp v23, v23, v23 row_half_mirror row_mask:0xf bank_mask:0xf
	v_pk_fma_f32 v[84:85], v[72:73], v[80:81], v[84:85] op_sel:[0,0,0] op_sel_hi:[0,1,1]
	v_pk_fma_f32 v[86:87], v[72:73], v[80:81], v[86:87] op_sel:[1,0,0] op_sel_hi:[1,1,1]
	v_add_f32_dpp v26, v26, v26 quad_perm:[1,0,3,2] row_mask:0xf bank_mask:0xf
	v_add_f32_dpp v22, v22, v22 row_mirror row_mask:0xf bank_mask:0xf
	v_add_f32_dpp v23, v23, v23 row_mirror row_mask:0xf bank_mask:0xf
	v_pk_fma_f32 v[88:89], v[74:75], v[80:81], v[88:89] op_sel:[0,0,0] op_sel_hi:[0,1,1]
	v_pk_fma_f32 v[90:91], v[74:75], v[80:81], v[90:91] op_sel:[1,0,0] op_sel_hi:[1,1,1]
	v_add_f32_dpp v26, v26, v26 quad_perm:[2,3,0,1] row_mask:0xf bank_mask:0xf
	v_cndmask_b32_e32 v31, v31, v26, vcc
	v_pk_fma_f32 v[2:3], v[68:69], v[22:23], v[84:85] op_sel:[0,0,0] op_sel_hi:[0,1,1] neg_lo:[1,0,0] neg_hi:[1,0,0]
	v_pk_fma_f32 v[4:5], v[68:69], v[22:23], v[86:87] op_sel:[1,0,0] op_sel_hi:[1,1,1] neg_lo:[1,0,0] neg_hi:[1,0,0]
	v_pk_fma_f32 v[6:7], v[70:71], v[22:23], v[88:89] op_sel:[0,0,0] op_sel_hi:[0,1,1] neg_lo:[1,0,0] neg_hi:[1,0,0]
	v_pk_fma_f32 v[8:9], v[70:71], v[22:23], v[90:91] op_sel:[1,0,0] op_sel_hi:[1,1,1] neg_lo:[1,0,0] neg_hi:[1,0,0]
	s_waitcnt lgkmcnt(0)
	v_pk_mul_f32 v[22:23], v[2:3], v[36:37] op_sel:[0,0] op_sel_hi:[1,0]
	v_pk_mul_f32 v[26:27], v[2:3], v[76:77] op_sel:[0,0] op_sel_hi:[1,0]
	ds_read_b128 v[60:63], v20 offset:4864
	v_pk_fma_f32 v[22:23], v[4:5], v[36:37], v[22:23] op_sel:[0,1,0] op_sel_hi:[1,1,1]
	v_pk_mul_f32 v[84:85], v[4:5], v[76:77] op_sel:[0,1] op_sel_hi:[1,1]
	ds_read_b128 v[64:67], v20 offset:13056
	v_pk_fma_f32 v[22:23], v[6:7], v[38:39], v[22:23] op_sel:[0,0,0] op_sel_hi:[1,0,1]
	v_pk_fma_f32 v[26:27], v[6:7], v[78:79], v[26:27] op_sel:[0,0,0] op_sel_hi:[1,0,1]
	ds_read_b64 v[80:81], v21 offset:45824
	v_pk_fma_f32 v[22:23], v[8:9], v[38:39], v[22:23] op_sel:[0,1,0] op_sel_hi:[1,1,1]
	v_pk_fma_f32 v[84:85], v[8:9], v[78:79], v[84:85] op_sel:[0,1,0] op_sel_hi:[1,1,1]
	ds_read_b128 v[72:75], v20 offset:29440
	v_pk_add_f32 v[26:27], v[26:27], v[84:85]
	ds_read_b128 v[68:71], v20 offset:21248
	ds_read_b128 v[76:79], v20 offset:37632
	v_add_f32_dpp v24, v24, v24 row_ror:12 row_mask:0xf bank_mask:0x5
	v_add_f32_dpp v25, v25, v25 row_ror:4 row_mask:0xf bank_mask:0xa
	v_add_f32_dpp v22, v22, v22 quad_perm:[1,0,3,2] row_mask:0xf bank_mask:0xf
	v_add_f32_dpp v23, v23, v23 quad_perm:[1,0,3,2] row_mask:0xf bank_mask:0xf
	v_pk_mul_f32 v[84:85], v[2:3], v[40:41] op_sel:[0,0] op_sel_hi:[1,0]
	v_pk_mul_f32 v[86:87], v[4:5], v[40:41] op_sel:[0,1] op_sel_hi:[1,1]
	v_mov_b32_dpp v24, v25 quad_perm:[0,1,2,3] row_mask:0xf bank_mask:0xa
	v_add_f32_dpp v22, v22, v22 quad_perm:[2,3,0,1] row_mask:0xf bank_mask:0xf
	v_add_f32_dpp v23, v23, v23 quad_perm:[2,3,0,1] row_mask:0xf bank_mask:0xf
	v_pk_mul_f32 v[88:89], v[6:7], v[42:43] op_sel:[0,0] op_sel_hi:[1,0]
	v_pk_mul_f32 v[90:91], v[8:9], v[42:43] op_sel:[0,1] op_sel_hi:[1,1]
	v_add_f32_dpp v24, v24, v24 row_ror:8 row_mask:0xf bank_mask:0xf
	v_add_f32_dpp v22, v22, v22 row_half_mirror row_mask:0xf bank_mask:0xf
	v_add_f32_dpp v23, v23, v23 row_half_mirror row_mask:0xf bank_mask:0xf
	v_pk_fma_f32 v[84:85], v[48:49], v[56:57], v[84:85] op_sel:[0,0,0] op_sel_hi:[0,1,1]
	v_pk_fma_f32 v[86:87], v[48:49], v[56:57], v[86:87] op_sel:[1,0,0] op_sel_hi:[1,1,1]
	v_add_f32_dpp v24, v24, v24 quad_perm:[1,0,3,2] row_mask:0xf bank_mask:0xf
	v_add_f32_dpp v22, v22, v22 row_mirror row_mask:0xf bank_mask:0xf
	v_add_f32_dpp v23, v23, v23 row_mirror row_mask:0xf bank_mask:0xf
	v_pk_fma_f32 v[88:89], v[50:51], v[56:57], v[88:89] op_sel:[0,0,0] op_sel_hi:[0,1,1]
	v_pk_fma_f32 v[90:91], v[50:51], v[56:57], v[90:91] op_sel:[1,0,0] op_sel_hi:[1,1,1]
	v_add_f32_dpp v24, v24, v24 quad_perm:[2,3,0,1] row_mask:0xf bank_mask:0xf
	v_cndmask_b32_e64 v32, 0, v24, s[0:1]
	v_pk_fma_f32 v[2:3], v[44:45], v[22:23], v[84:85] op_sel:[0,0,0] op_sel_hi:[0,1,1] neg_lo:[1,0,0] neg_hi:[1,0,0]
	v_pk_fma_f32 v[4:5], v[44:45], v[22:23], v[86:87] op_sel:[1,0,0] op_sel_hi:[1,1,1] neg_lo:[1,0,0] neg_hi:[1,0,0]
	v_pk_fma_f32 v[6:7], v[46:47], v[22:23], v[88:89] op_sel:[0,0,0] op_sel_hi:[0,1,1] neg_lo:[1,0,0] neg_hi:[1,0,0]
	v_pk_fma_f32 v[8:9], v[46:47], v[22:23], v[90:91] op_sel:[1,0,0] op_sel_hi:[1,1,1] neg_lo:[1,0,0] neg_hi:[1,0,0]
	s_waitcnt lgkmcnt(0)
	v_pk_mul_f32 v[22:23], v[2:3], v[60:61] op_sel:[0,0] op_sel_hi:[1,0]
	v_pk_mul_f32 v[24:25], v[2:3], v[52:53] op_sel:[0,0] op_sel_hi:[1,0]
	ds_read_b128 v[36:39], v20 offset:5120
	v_pk_fma_f32 v[22:23], v[4:5], v[60:61], v[22:23] op_sel:[0,1,0] op_sel_hi:[1,1,1]
	v_pk_mul_f32 v[84:85], v[4:5], v[52:53] op_sel:[0,1] op_sel_hi:[1,1]
	ds_read_b128 v[40:43], v20 offset:13312
	v_pk_fma_f32 v[22:23], v[6:7], v[62:63], v[22:23] op_sel:[0,0,0] op_sel_hi:[1,0,1]
	v_pk_fma_f32 v[24:25], v[6:7], v[54:55], v[24:25] op_sel:[0,0,0] op_sel_hi:[1,0,1]
	ds_read_b64 v[56:57], v21 offset:46080
	v_pk_fma_f32 v[22:23], v[8:9], v[62:63], v[22:23] op_sel:[0,1,0] op_sel_hi:[1,1,1]
	v_pk_fma_f32 v[84:85], v[8:9], v[54:55], v[84:85] op_sel:[0,1,0] op_sel_hi:[1,1,1]
	ds_read_b128 v[48:51], v20 offset:29696
	v_pk_add_f32 v[24:25], v[24:25], v[84:85]
	ds_read_b128 v[44:47], v20 offset:21504
	ds_read_b128 v[52:55], v20 offset:37888
	v_add_f32_dpp v26, v26, v26 row_ror:12 row_mask:0xf bank_mask:0x5
	v_add_f32_dpp v27, v27, v27 row_ror:4 row_mask:0xf bank_mask:0xa
	v_add_f32_dpp v22, v22, v22 quad_perm:[1,0,3,2] row_mask:0xf bank_mask:0xf
	v_add_f32_dpp v23, v23, v23 quad_perm:[1,0,3,2] row_mask:0xf bank_mask:0xf
	v_pk_mul_f32 v[84:85], v[2:3], v[64:65] op_sel:[0,0] op_sel_hi:[1,0]
	v_pk_mul_f32 v[86:87], v[4:5], v[64:65] op_sel:[0,1] op_sel_hi:[1,1]
	v_mov_b32_dpp v26, v27 quad_perm:[0,1,2,3] row_mask:0xf bank_mask:0xa
	v_add_f32_dpp v22, v22, v22 quad_perm:[2,3,0,1] row_mask:0xf bank_mask:0xf
	v_add_f32_dpp v23, v23, v23 quad_perm:[2,3,0,1] row_mask:0xf bank_mask:0xf
	v_pk_mul_f32 v[88:89], v[6:7], v[66:67] op_sel:[0,0] op_sel_hi:[1,0]
	v_pk_mul_f32 v[90:91], v[8:9], v[66:67] op_sel:[0,1] op_sel_hi:[1,1]
	v_add_f32_dpp v26, v26, v26 row_ror:8 row_mask:0xf bank_mask:0xf
	v_add_f32_dpp v22, v22, v22 row_half_mirror row_mask:0xf bank_mask:0xf
	v_add_f32_dpp v23, v23, v23 row_half_mirror row_mask:0xf bank_mask:0xf
	v_pk_fma_f32 v[84:85], v[72:73], v[80:81], v[84:85] op_sel:[0,0,0] op_sel_hi:[0,1,1]
	v_pk_fma_f32 v[86:87], v[72:73], v[80:81], v[86:87] op_sel:[1,0,0] op_sel_hi:[1,1,1]
	v_add_f32_dpp v26, v26, v26 quad_perm:[1,0,3,2] row_mask:0xf bank_mask:0xf
	v_add_f32_dpp v22, v22, v22 row_mirror row_mask:0xf bank_mask:0xf
	v_add_f32_dpp v23, v23, v23 row_mirror row_mask:0xf bank_mask:0xf
	v_pk_fma_f32 v[88:89], v[74:75], v[80:81], v[88:89] op_sel:[0,0,0] op_sel_hi:[0,1,1]
	v_pk_fma_f32 v[90:91], v[74:75], v[80:81], v[90:91] op_sel:[1,0,0] op_sel_hi:[1,1,1]
	v_add_f32_dpp v26, v26, v26 quad_perm:[2,3,0,1] row_mask:0xf bank_mask:0xf
	v_cndmask_b32_e64 v32, v32, v26, s[6:7]
	v_pk_fma_f32 v[2:3], v[68:69], v[22:23], v[84:85] op_sel:[0,0,0] op_sel_hi:[0,1,1] neg_lo:[1,0,0] neg_hi:[1,0,0]
	v_pk_fma_f32 v[4:5], v[68:69], v[22:23], v[86:87] op_sel:[1,0,0] op_sel_hi:[1,1,1] neg_lo:[1,0,0] neg_hi:[1,0,0]
	v_pk_fma_f32 v[6:7], v[70:71], v[22:23], v[88:89] op_sel:[0,0,0] op_sel_hi:[0,1,1] neg_lo:[1,0,0] neg_hi:[1,0,0]
	v_pk_fma_f32 v[8:9], v[70:71], v[22:23], v[90:91] op_sel:[1,0,0] op_sel_hi:[1,1,1] neg_lo:[1,0,0] neg_hi:[1,0,0]
	s_waitcnt lgkmcnt(0)
	v_pk_mul_f32 v[22:23], v[2:3], v[36:37] op_sel:[0,0] op_sel_hi:[1,0]
	v_pk_mul_f32 v[26:27], v[2:3], v[76:77] op_sel:[0,0] op_sel_hi:[1,0]
	ds_read_b128 v[60:63], v20 offset:5376
	v_pk_fma_f32 v[22:23], v[4:5], v[36:37], v[22:23] op_sel:[0,1,0] op_sel_hi:[1,1,1]
	v_pk_mul_f32 v[84:85], v[4:5], v[76:77] op_sel:[0,1] op_sel_hi:[1,1]
	ds_read_b128 v[64:67], v20 offset:13568
	v_pk_fma_f32 v[22:23], v[6:7], v[38:39], v[22:23] op_sel:[0,0,0] op_sel_hi:[1,0,1]
	v_pk_fma_f32 v[26:27], v[6:7], v[78:79], v[26:27] op_sel:[0,0,0] op_sel_hi:[1,0,1]
	ds_read_b64 v[80:81], v21 offset:46336
	v_pk_fma_f32 v[22:23], v[8:9], v[38:39], v[22:23] op_sel:[0,1,0] op_sel_hi:[1,1,1]
	v_pk_fma_f32 v[84:85], v[8:9], v[78:79], v[84:85] op_sel:[0,1,0] op_sel_hi:[1,1,1]
	ds_read_b128 v[72:75], v20 offset:29952
	v_pk_add_f32 v[26:27], v[26:27], v[84:85]
	ds_read_b128 v[68:71], v20 offset:21760
	ds_read_b128 v[76:79], v20 offset:38144
	v_add_f32_dpp v24, v24, v24 row_ror:12 row_mask:0xf bank_mask:0x5
	v_add_f32_dpp v25, v25, v25 row_ror:4 row_mask:0xf bank_mask:0xa
	v_add_f32_dpp v22, v22, v22 quad_perm:[1,0,3,2] row_mask:0xf bank_mask:0xf
	v_add_f32_dpp v23, v23, v23 quad_perm:[1,0,3,2] row_mask:0xf bank_mask:0xf
	v_pk_mul_f32 v[84:85], v[2:3], v[40:41] op_sel:[0,0] op_sel_hi:[1,0]
	v_pk_mul_f32 v[86:87], v[4:5], v[40:41] op_sel:[0,1] op_sel_hi:[1,1]
	v_mov_b32_dpp v24, v25 quad_perm:[0,1,2,3] row_mask:0xf bank_mask:0xa
	v_add_f32_dpp v22, v22, v22 quad_perm:[2,3,0,1] row_mask:0xf bank_mask:0xf
	v_add_f32_dpp v23, v23, v23 quad_perm:[2,3,0,1] row_mask:0xf bank_mask:0xf
	v_pk_mul_f32 v[88:89], v[6:7], v[42:43] op_sel:[0,0] op_sel_hi:[1,0]
	v_pk_mul_f32 v[90:91], v[8:9], v[42:43] op_sel:[0,1] op_sel_hi:[1,1]
	v_add_f32_dpp v24, v24, v24 row_ror:8 row_mask:0xf bank_mask:0xf
	v_add_f32_dpp v22, v22, v22 row_half_mirror row_mask:0xf bank_mask:0xf
	v_add_f32_dpp v23, v23, v23 row_half_mirror row_mask:0xf bank_mask:0xf
	v_pk_fma_f32 v[84:85], v[48:49], v[56:57], v[84:85] op_sel:[0,0,0] op_sel_hi:[0,1,1]
	v_pk_fma_f32 v[86:87], v[48:49], v[56:57], v[86:87] op_sel:[1,0,0] op_sel_hi:[1,1,1]
	v_add_f32_dpp v24, v24, v24 quad_perm:[1,0,3,2] row_mask:0xf bank_mask:0xf
	v_add_f32_dpp v22, v22, v22 row_mirror row_mask:0xf bank_mask:0xf
	v_add_f32_dpp v23, v23, v23 row_mirror row_mask:0xf bank_mask:0xf
	v_pk_fma_f32 v[88:89], v[50:51], v[56:57], v[88:89] op_sel:[0,0,0] op_sel_hi:[0,1,1]
	v_pk_fma_f32 v[90:91], v[50:51], v[56:57], v[90:91] op_sel:[1,0,0] op_sel_hi:[1,1,1]
	v_add_f32_dpp v24, v24, v24 quad_perm:[2,3,0,1] row_mask:0xf bank_mask:0xf
	v_cndmask_b32_e64 v32, v32, v24, s[8:9]
	v_pk_fma_f32 v[2:3], v[44:45], v[22:23], v[84:85] op_sel:[0,0,0] op_sel_hi:[0,1,1] neg_lo:[1,0,0] neg_hi:[1,0,0]
	v_pk_fma_f32 v[4:5], v[44:45], v[22:23], v[86:87] op_sel:[1,0,0] op_sel_hi:[1,1,1] neg_lo:[1,0,0] neg_hi:[1,0,0]
	v_pk_fma_f32 v[6:7], v[46:47], v[22:23], v[88:89] op_sel:[0,0,0] op_sel_hi:[0,1,1] neg_lo:[1,0,0] neg_hi:[1,0,0]
	v_pk_fma_f32 v[8:9], v[46:47], v[22:23], v[90:91] op_sel:[1,0,0] op_sel_hi:[1,1,1] neg_lo:[1,0,0] neg_hi:[1,0,0]
	s_waitcnt lgkmcnt(0)
	v_pk_mul_f32 v[22:23], v[2:3], v[60:61] op_sel:[0,0] op_sel_hi:[1,0]
	v_pk_mul_f32 v[24:25], v[2:3], v[52:53] op_sel:[0,0] op_sel_hi:[1,0]
	ds_read_b128 v[36:39], v20 offset:5632
	v_pk_fma_f32 v[22:23], v[4:5], v[60:61], v[22:23] op_sel:[0,1,0] op_sel_hi:[1,1,1]
	v_pk_mul_f32 v[84:85], v[4:5], v[52:53] op_sel:[0,1] op_sel_hi:[1,1]
	ds_read_b128 v[40:43], v20 offset:13824
	v_pk_fma_f32 v[22:23], v[6:7], v[62:63], v[22:23] op_sel:[0,0,0] op_sel_hi:[1,0,1]
	v_pk_fma_f32 v[24:25], v[6:7], v[54:55], v[24:25] op_sel:[0,0,0] op_sel_hi:[1,0,1]
	ds_read_b64 v[56:57], v21 offset:46592
	v_pk_fma_f32 v[22:23], v[8:9], v[62:63], v[22:23] op_sel:[0,1,0] op_sel_hi:[1,1,1]
	v_pk_fma_f32 v[84:85], v[8:9], v[54:55], v[84:85] op_sel:[0,1,0] op_sel_hi:[1,1,1]
	ds_read_b128 v[48:51], v20 offset:30208
	v_pk_add_f32 v[24:25], v[24:25], v[84:85]
	ds_read_b128 v[44:47], v20 offset:22016
	ds_read_b128 v[52:55], v20 offset:38400
	v_add_f32_dpp v26, v26, v26 row_ror:12 row_mask:0xf bank_mask:0x5
	v_add_f32_dpp v27, v27, v27 row_ror:4 row_mask:0xf bank_mask:0xa
	v_add_f32_dpp v22, v22, v22 quad_perm:[1,0,3,2] row_mask:0xf bank_mask:0xf
	v_add_f32_dpp v23, v23, v23 quad_perm:[1,0,3,2] row_mask:0xf bank_mask:0xf
	v_pk_mul_f32 v[84:85], v[2:3], v[64:65] op_sel:[0,0] op_sel_hi:[1,0]
	v_pk_mul_f32 v[86:87], v[4:5], v[64:65] op_sel:[0,1] op_sel_hi:[1,1]
	v_mov_b32_dpp v26, v27 quad_perm:[0,1,2,3] row_mask:0xf bank_mask:0xa
	v_add_f32_dpp v22, v22, v22 quad_perm:[2,3,0,1] row_mask:0xf bank_mask:0xf
	v_add_f32_dpp v23, v23, v23 quad_perm:[2,3,0,1] row_mask:0xf bank_mask:0xf
	v_pk_mul_f32 v[88:89], v[6:7], v[66:67] op_sel:[0,0] op_sel_hi:[1,0]
	v_pk_mul_f32 v[90:91], v[8:9], v[66:67] op_sel:[0,1] op_sel_hi:[1,1]
	v_add_f32_dpp v26, v26, v26 row_ror:8 row_mask:0xf bank_mask:0xf
	v_add_f32_dpp v22, v22, v22 row_half_mirror row_mask:0xf bank_mask:0xf
	v_add_f32_dpp v23, v23, v23 row_half_mirror row_mask:0xf bank_mask:0xf
	v_pk_fma_f32 v[84:85], v[72:73], v[80:81], v[84:85] op_sel:[0,0,0] op_sel_hi:[0,1,1]
	v_pk_fma_f32 v[86:87], v[72:73], v[80:81], v[86:87] op_sel:[1,0,0] op_sel_hi:[1,1,1]
	v_add_f32_dpp v26, v26, v26 quad_perm:[1,0,3,2] row_mask:0xf bank_mask:0xf
	v_add_f32_dpp v22, v22, v22 row_mirror row_mask:0xf bank_mask:0xf
	v_add_f32_dpp v23, v23, v23 row_mirror row_mask:0xf bank_mask:0xf
	v_pk_fma_f32 v[88:89], v[74:75], v[80:81], v[88:89] op_sel:[0,0,0] op_sel_hi:[0,1,1]
	v_pk_fma_f32 v[90:91], v[74:75], v[80:81], v[90:91] op_sel:[1,0,0] op_sel_hi:[1,1,1]
	v_add_f32_dpp v26, v26, v26 quad_perm:[2,3,0,1] row_mask:0xf bank_mask:0xf
	v_cndmask_b32_e64 v32, v32, v26, s[10:11]
	v_pk_fma_f32 v[2:3], v[68:69], v[22:23], v[84:85] op_sel:[0,0,0] op_sel_hi:[0,1,1] neg_lo:[1,0,0] neg_hi:[1,0,0]
	v_pk_fma_f32 v[4:5], v[68:69], v[22:23], v[86:87] op_sel:[1,0,0] op_sel_hi:[1,1,1] neg_lo:[1,0,0] neg_hi:[1,0,0]
	v_pk_fma_f32 v[6:7], v[70:71], v[22:23], v[88:89] op_sel:[0,0,0] op_sel_hi:[0,1,1] neg_lo:[1,0,0] neg_hi:[1,0,0]
	v_pk_fma_f32 v[8:9], v[70:71], v[22:23], v[90:91] op_sel:[1,0,0] op_sel_hi:[1,1,1] neg_lo:[1,0,0] neg_hi:[1,0,0]
	s_waitcnt lgkmcnt(0)
	v_pk_mul_f32 v[22:23], v[2:3], v[36:37] op_sel:[0,0] op_sel_hi:[1,0]
	v_pk_mul_f32 v[26:27], v[2:3], v[76:77] op_sel:[0,0] op_sel_hi:[1,0]
	ds_read_b128 v[60:63], v20 offset:5888
	v_pk_fma_f32 v[22:23], v[4:5], v[36:37], v[22:23] op_sel:[0,1,0] op_sel_hi:[1,1,1]
	v_pk_mul_f32 v[84:85], v[4:5], v[76:77] op_sel:[0,1] op_sel_hi:[1,1]
	ds_read_b128 v[64:67], v20 offset:14080
	v_pk_fma_f32 v[22:23], v[6:7], v[38:39], v[22:23] op_sel:[0,0,0] op_sel_hi:[1,0,1]
	v_pk_fma_f32 v[26:27], v[6:7], v[78:79], v[26:27] op_sel:[0,0,0] op_sel_hi:[1,0,1]
	ds_read_b64 v[80:81], v21 offset:46848
	v_pk_fma_f32 v[22:23], v[8:9], v[38:39], v[22:23] op_sel:[0,1,0] op_sel_hi:[1,1,1]
	v_pk_fma_f32 v[84:85], v[8:9], v[78:79], v[84:85] op_sel:[0,1,0] op_sel_hi:[1,1,1]
	ds_read_b128 v[72:75], v20 offset:30464
	v_pk_add_f32 v[26:27], v[26:27], v[84:85]
	ds_read_b128 v[68:71], v20 offset:22272
	ds_read_b128 v[76:79], v20 offset:38656
	v_add_f32_dpp v24, v24, v24 row_ror:12 row_mask:0xf bank_mask:0x5
	v_add_f32_dpp v25, v25, v25 row_ror:4 row_mask:0xf bank_mask:0xa
	v_add_f32_dpp v22, v22, v22 quad_perm:[1,0,3,2] row_mask:0xf bank_mask:0xf
	v_add_f32_dpp v23, v23, v23 quad_perm:[1,0,3,2] row_mask:0xf bank_mask:0xf
	v_pk_mul_f32 v[84:85], v[2:3], v[40:41] op_sel:[0,0] op_sel_hi:[1,0]
	v_pk_mul_f32 v[86:87], v[4:5], v[40:41] op_sel:[0,1] op_sel_hi:[1,1]
	v_mov_b32_dpp v24, v25 quad_perm:[0,1,2,3] row_mask:0xf bank_mask:0xa
	v_add_f32_dpp v22, v22, v22 quad_perm:[2,3,0,1] row_mask:0xf bank_mask:0xf
	v_add_f32_dpp v23, v23, v23 quad_perm:[2,3,0,1] row_mask:0xf bank_mask:0xf
	v_pk_mul_f32 v[88:89], v[6:7], v[42:43] op_sel:[0,0] op_sel_hi:[1,0]
	v_pk_mul_f32 v[90:91], v[8:9], v[42:43] op_sel:[0,1] op_sel_hi:[1,1]
	v_add_f32_dpp v24, v24, v24 row_ror:8 row_mask:0xf bank_mask:0xf
	v_add_f32_dpp v22, v22, v22 row_half_mirror row_mask:0xf bank_mask:0xf
	v_add_f32_dpp v23, v23, v23 row_half_mirror row_mask:0xf bank_mask:0xf
	v_pk_fma_f32 v[84:85], v[48:49], v[56:57], v[84:85] op_sel:[0,0,0] op_sel_hi:[0,1,1]
	v_pk_fma_f32 v[86:87], v[48:49], v[56:57], v[86:87] op_sel:[1,0,0] op_sel_hi:[1,1,1]
	v_add_f32_dpp v24, v24, v24 quad_perm:[1,0,3,2] row_mask:0xf bank_mask:0xf
	v_add_f32_dpp v22, v22, v22 row_mirror row_mask:0xf bank_mask:0xf
	v_add_f32_dpp v23, v23, v23 row_mirror row_mask:0xf bank_mask:0xf
	v_pk_fma_f32 v[88:89], v[50:51], v[56:57], v[88:89] op_sel:[0,0,0] op_sel_hi:[0,1,1]
	v_pk_fma_f32 v[90:91], v[50:51], v[56:57], v[90:91] op_sel:[1,0,0] op_sel_hi:[1,1,1]
	v_add_f32_dpp v24, v24, v24 quad_perm:[2,3,0,1] row_mask:0xf bank_mask:0xf
	v_cndmask_b32_e64 v32, v32, v24, s[12:13]
	v_pk_fma_f32 v[2:3], v[44:45], v[22:23], v[84:85] op_sel:[0,0,0] op_sel_hi:[0,1,1] neg_lo:[1,0,0] neg_hi:[1,0,0]
	v_pk_fma_f32 v[4:5], v[44:45], v[22:23], v[86:87] op_sel:[1,0,0] op_sel_hi:[1,1,1] neg_lo:[1,0,0] neg_hi:[1,0,0]
	v_pk_fma_f32 v[6:7], v[46:47], v[22:23], v[88:89] op_sel:[0,0,0] op_sel_hi:[0,1,1] neg_lo:[1,0,0] neg_hi:[1,0,0]
	v_pk_fma_f32 v[8:9], v[46:47], v[22:23], v[90:91] op_sel:[1,0,0] op_sel_hi:[1,1,1] neg_lo:[1,0,0] neg_hi:[1,0,0]
	s_waitcnt lgkmcnt(0)
	v_pk_mul_f32 v[22:23], v[2:3], v[60:61] op_sel:[0,0] op_sel_hi:[1,0]
	v_pk_mul_f32 v[24:25], v[2:3], v[52:53] op_sel:[0,0] op_sel_hi:[1,0]
	ds_read_b128 v[36:39], v20 offset:6144
	v_pk_fma_f32 v[22:23], v[4:5], v[60:61], v[22:23] op_sel:[0,1,0] op_sel_hi:[1,1,1]
	v_pk_mul_f32 v[84:85], v[4:5], v[52:53] op_sel:[0,1] op_sel_hi:[1,1]
	ds_read_b128 v[40:43], v20 offset:14336
	v_pk_fma_f32 v[22:23], v[6:7], v[62:63], v[22:23] op_sel:[0,0,0] op_sel_hi:[1,0,1]
	v_pk_fma_f32 v[24:25], v[6:7], v[54:55], v[24:25] op_sel:[0,0,0] op_sel_hi:[1,0,1]
	ds_read_b64 v[56:57], v21 offset:47104
	v_pk_fma_f32 v[22:23], v[8:9], v[62:63], v[22:23] op_sel:[0,1,0] op_sel_hi:[1,1,1]
	v_pk_fma_f32 v[84:85], v[8:9], v[54:55], v[84:85] op_sel:[0,1,0] op_sel_hi:[1,1,1]
	ds_read_b128 v[48:51], v20 offset:30720
	v_pk_add_f32 v[24:25], v[24:25], v[84:85]
	ds_read_b128 v[44:47], v20 offset:22528
	ds_read_b128 v[52:55], v20 offset:38912
	v_add_f32_dpp v26, v26, v26 row_ror:12 row_mask:0xf bank_mask:0x5
	v_add_f32_dpp v27, v27, v27 row_ror:4 row_mask:0xf bank_mask:0xa
	v_add_f32_dpp v22, v22, v22 quad_perm:[1,0,3,2] row_mask:0xf bank_mask:0xf
	v_add_f32_dpp v23, v23, v23 quad_perm:[1,0,3,2] row_mask:0xf bank_mask:0xf
	v_pk_mul_f32 v[84:85], v[2:3], v[64:65] op_sel:[0,0] op_sel_hi:[1,0]
	v_pk_mul_f32 v[86:87], v[4:5], v[64:65] op_sel:[0,1] op_sel_hi:[1,1]
	v_mov_b32_dpp v26, v27 quad_perm:[0,1,2,3] row_mask:0xf bank_mask:0xa
	v_add_f32_dpp v22, v22, v22 quad_perm:[2,3,0,1] row_mask:0xf bank_mask:0xf
	v_add_f32_dpp v23, v23, v23 quad_perm:[2,3,0,1] row_mask:0xf bank_mask:0xf
	v_pk_mul_f32 v[88:89], v[6:7], v[66:67] op_sel:[0,0] op_sel_hi:[1,0]
	v_pk_mul_f32 v[90:91], v[8:9], v[66:67] op_sel:[0,1] op_sel_hi:[1,1]
	v_add_f32_dpp v26, v26, v26 row_ror:8 row_mask:0xf bank_mask:0xf
	v_add_f32_dpp v22, v22, v22 row_half_mirror row_mask:0xf bank_mask:0xf
	v_add_f32_dpp v23, v23, v23 row_half_mirror row_mask:0xf bank_mask:0xf
	v_pk_fma_f32 v[84:85], v[72:73], v[80:81], v[84:85] op_sel:[0,0,0] op_sel_hi:[0,1,1]
	v_pk_fma_f32 v[86:87], v[72:73], v[80:81], v[86:87] op_sel:[1,0,0] op_sel_hi:[1,1,1]
	v_add_f32_dpp v26, v26, v26 quad_perm:[1,0,3,2] row_mask:0xf bank_mask:0xf
	v_add_f32_dpp v22, v22, v22 row_mirror row_mask:0xf bank_mask:0xf
	v_add_f32_dpp v23, v23, v23 row_mirror row_mask:0xf bank_mask:0xf
	v_pk_fma_f32 v[88:89], v[74:75], v[80:81], v[88:89] op_sel:[0,0,0] op_sel_hi:[0,1,1]
	v_pk_fma_f32 v[90:91], v[74:75], v[80:81], v[90:91] op_sel:[1,0,0] op_sel_hi:[1,1,1]
	v_add_f32_dpp v26, v26, v26 quad_perm:[2,3,0,1] row_mask:0xf bank_mask:0xf
	v_cndmask_b32_e64 v32, v32, v26, s[14:15]
	v_pk_fma_f32 v[2:3], v[68:69], v[22:23], v[84:85] op_sel:[0,0,0] op_sel_hi:[0,1,1] neg_lo:[1,0,0] neg_hi:[1,0,0]
	v_pk_fma_f32 v[4:5], v[68:69], v[22:23], v[86:87] op_sel:[1,0,0] op_sel_hi:[1,1,1] neg_lo:[1,0,0] neg_hi:[1,0,0]
	v_pk_fma_f32 v[6:7], v[70:71], v[22:23], v[88:89] op_sel:[0,0,0] op_sel_hi:[0,1,1] neg_lo:[1,0,0] neg_hi:[1,0,0]
	v_pk_fma_f32 v[8:9], v[70:71], v[22:23], v[90:91] op_sel:[1,0,0] op_sel_hi:[1,1,1] neg_lo:[1,0,0] neg_hi:[1,0,0]
	s_waitcnt lgkmcnt(0)
	v_pk_mul_f32 v[22:23], v[2:3], v[36:37] op_sel:[0,0] op_sel_hi:[1,0]
	v_pk_mul_f32 v[26:27], v[2:3], v[76:77] op_sel:[0,0] op_sel_hi:[1,0]
	ds_read_b128 v[60:63], v20 offset:6400
	v_pk_fma_f32 v[22:23], v[4:5], v[36:37], v[22:23] op_sel:[0,1,0] op_sel_hi:[1,1,1]
	v_pk_mul_f32 v[84:85], v[4:5], v[76:77] op_sel:[0,1] op_sel_hi:[1,1]
	ds_read_b128 v[64:67], v20 offset:14592
	v_pk_fma_f32 v[22:23], v[6:7], v[38:39], v[22:23] op_sel:[0,0,0] op_sel_hi:[1,0,1]
	v_pk_fma_f32 v[26:27], v[6:7], v[78:79], v[26:27] op_sel:[0,0,0] op_sel_hi:[1,0,1]
	ds_read_b64 v[80:81], v21 offset:47360
	v_pk_fma_f32 v[22:23], v[8:9], v[38:39], v[22:23] op_sel:[0,1,0] op_sel_hi:[1,1,1]
	v_pk_fma_f32 v[84:85], v[8:9], v[78:79], v[84:85] op_sel:[0,1,0] op_sel_hi:[1,1,1]
	ds_read_b128 v[72:75], v20 offset:30976
	v_pk_add_f32 v[26:27], v[26:27], v[84:85]
	ds_read_b128 v[68:71], v20 offset:22784
	ds_read_b128 v[76:79], v20 offset:39168
	v_add_f32_dpp v24, v24, v24 row_ror:12 row_mask:0xf bank_mask:0x5
	v_add_f32_dpp v25, v25, v25 row_ror:4 row_mask:0xf bank_mask:0xa
	v_add_f32_dpp v22, v22, v22 quad_perm:[1,0,3,2] row_mask:0xf bank_mask:0xf
	v_add_f32_dpp v23, v23, v23 quad_perm:[1,0,3,2] row_mask:0xf bank_mask:0xf
	v_pk_mul_f32 v[84:85], v[2:3], v[40:41] op_sel:[0,0] op_sel_hi:[1,0]
	v_pk_mul_f32 v[86:87], v[4:5], v[40:41] op_sel:[0,1] op_sel_hi:[1,1]
	v_mov_b32_dpp v24, v25 quad_perm:[0,1,2,3] row_mask:0xf bank_mask:0xa
	v_add_f32_dpp v22, v22, v22 quad_perm:[2,3,0,1] row_mask:0xf bank_mask:0xf
	v_add_f32_dpp v23, v23, v23 quad_perm:[2,3,0,1] row_mask:0xf bank_mask:0xf
	v_pk_mul_f32 v[88:89], v[6:7], v[42:43] op_sel:[0,0] op_sel_hi:[1,0]
	v_pk_mul_f32 v[90:91], v[8:9], v[42:43] op_sel:[0,1] op_sel_hi:[1,1]
	v_add_f32_dpp v24, v24, v24 row_ror:8 row_mask:0xf bank_mask:0xf
	v_add_f32_dpp v22, v22, v22 row_half_mirror row_mask:0xf bank_mask:0xf
	v_add_f32_dpp v23, v23, v23 row_half_mirror row_mask:0xf bank_mask:0xf
	v_pk_fma_f32 v[84:85], v[48:49], v[56:57], v[84:85] op_sel:[0,0,0] op_sel_hi:[0,1,1]
	v_pk_fma_f32 v[86:87], v[48:49], v[56:57], v[86:87] op_sel:[1,0,0] op_sel_hi:[1,1,1]
	v_add_f32_dpp v24, v24, v24 quad_perm:[1,0,3,2] row_mask:0xf bank_mask:0xf
	v_add_f32_dpp v22, v22, v22 row_mirror row_mask:0xf bank_mask:0xf
	v_add_f32_dpp v23, v23, v23 row_mirror row_mask:0xf bank_mask:0xf
	v_pk_fma_f32 v[88:89], v[50:51], v[56:57], v[88:89] op_sel:[0,0,0] op_sel_hi:[0,1,1]
	v_pk_fma_f32 v[90:91], v[50:51], v[56:57], v[90:91] op_sel:[1,0,0] op_sel_hi:[1,1,1]
	v_add_f32_dpp v24, v24, v24 quad_perm:[2,3,0,1] row_mask:0xf bank_mask:0xf
	v_cndmask_b32_e64 v32, v32, v24, s[16:17]
	v_pk_fma_f32 v[2:3], v[44:45], v[22:23], v[84:85] op_sel:[0,0,0] op_sel_hi:[0,1,1] neg_lo:[1,0,0] neg_hi:[1,0,0]
	v_pk_fma_f32 v[4:5], v[44:45], v[22:23], v[86:87] op_sel:[1,0,0] op_sel_hi:[1,1,1] neg_lo:[1,0,0] neg_hi:[1,0,0]
	v_pk_fma_f32 v[6:7], v[46:47], v[22:23], v[88:89] op_sel:[0,0,0] op_sel_hi:[0,1,1] neg_lo:[1,0,0] neg_hi:[1,0,0]
	v_pk_fma_f32 v[8:9], v[46:47], v[22:23], v[90:91] op_sel:[1,0,0] op_sel_hi:[1,1,1] neg_lo:[1,0,0] neg_hi:[1,0,0]
	s_waitcnt lgkmcnt(0)
	v_pk_mul_f32 v[22:23], v[2:3], v[60:61] op_sel:[0,0] op_sel_hi:[1,0]
	v_pk_mul_f32 v[24:25], v[2:3], v[52:53] op_sel:[0,0] op_sel_hi:[1,0]
	ds_read_b128 v[36:39], v20 offset:6656
	v_pk_fma_f32 v[22:23], v[4:5], v[60:61], v[22:23] op_sel:[0,1,0] op_sel_hi:[1,1,1]
	v_pk_mul_f32 v[84:85], v[4:5], v[52:53] op_sel:[0,1] op_sel_hi:[1,1]
	ds_read_b128 v[40:43], v20 offset:14848
	v_pk_fma_f32 v[22:23], v[6:7], v[62:63], v[22:23] op_sel:[0,0,0] op_sel_hi:[1,0,1]
	v_pk_fma_f32 v[24:25], v[6:7], v[54:55], v[24:25] op_sel:[0,0,0] op_sel_hi:[1,0,1]
	ds_read_b64 v[56:57], v21 offset:47616
	v_pk_fma_f32 v[22:23], v[8:9], v[62:63], v[22:23] op_sel:[0,1,0] op_sel_hi:[1,1,1]
	v_pk_fma_f32 v[84:85], v[8:9], v[54:55], v[84:85] op_sel:[0,1,0] op_sel_hi:[1,1,1]
	ds_read_b128 v[48:51], v20 offset:31232
	v_pk_add_f32 v[24:25], v[24:25], v[84:85]
	ds_read_b128 v[44:47], v20 offset:23040
	ds_read_b128 v[52:55], v20 offset:39424
	v_add_f32_dpp v26, v26, v26 row_ror:12 row_mask:0xf bank_mask:0x5
	v_add_f32_dpp v27, v27, v27 row_ror:4 row_mask:0xf bank_mask:0xa
	v_add_f32_dpp v22, v22, v22 quad_perm:[1,0,3,2] row_mask:0xf bank_mask:0xf
	v_add_f32_dpp v23, v23, v23 quad_perm:[1,0,3,2] row_mask:0xf bank_mask:0xf
	v_pk_mul_f32 v[84:85], v[2:3], v[64:65] op_sel:[0,0] op_sel_hi:[1,0]
	v_pk_mul_f32 v[86:87], v[4:5], v[64:65] op_sel:[0,1] op_sel_hi:[1,1]
	v_mov_b32_dpp v26, v27 quad_perm:[0,1,2,3] row_mask:0xf bank_mask:0xa
	v_add_f32_dpp v22, v22, v22 quad_perm:[2,3,0,1] row_mask:0xf bank_mask:0xf
	v_add_f32_dpp v23, v23, v23 quad_perm:[2,3,0,1] row_mask:0xf bank_mask:0xf
	v_pk_mul_f32 v[88:89], v[6:7], v[66:67] op_sel:[0,0] op_sel_hi:[1,0]
	v_pk_mul_f32 v[90:91], v[8:9], v[66:67] op_sel:[0,1] op_sel_hi:[1,1]
	v_add_f32_dpp v26, v26, v26 row_ror:8 row_mask:0xf bank_mask:0xf
	v_add_f32_dpp v22, v22, v22 row_half_mirror row_mask:0xf bank_mask:0xf
	v_add_f32_dpp v23, v23, v23 row_half_mirror row_mask:0xf bank_mask:0xf
	v_pk_fma_f32 v[84:85], v[72:73], v[80:81], v[84:85] op_sel:[0,0,0] op_sel_hi:[0,1,1]
	v_pk_fma_f32 v[86:87], v[72:73], v[80:81], v[86:87] op_sel:[1,0,0] op_sel_hi:[1,1,1]
	v_add_f32_dpp v26, v26, v26 quad_perm:[1,0,3,2] row_mask:0xf bank_mask:0xf
	v_add_f32_dpp v22, v22, v22 row_mirror row_mask:0xf bank_mask:0xf
	v_add_f32_dpp v23, v23, v23 row_mirror row_mask:0xf bank_mask:0xf
	v_pk_fma_f32 v[88:89], v[74:75], v[80:81], v[88:89] op_sel:[0,0,0] op_sel_hi:[0,1,1]
	v_pk_fma_f32 v[90:91], v[74:75], v[80:81], v[90:91] op_sel:[1,0,0] op_sel_hi:[1,1,1]
	v_add_f32_dpp v26, v26, v26 quad_perm:[2,3,0,1] row_mask:0xf bank_mask:0xf
	v_cndmask_b32_e32 v32, v32, v26, vcc
	v_pk_fma_f32 v[2:3], v[68:69], v[22:23], v[84:85] op_sel:[0,0,0] op_sel_hi:[0,1,1] neg_lo:[1,0,0] neg_hi:[1,0,0]
	v_pk_fma_f32 v[4:5], v[68:69], v[22:23], v[86:87] op_sel:[1,0,0] op_sel_hi:[1,1,1] neg_lo:[1,0,0] neg_hi:[1,0,0]
	v_pk_fma_f32 v[6:7], v[70:71], v[22:23], v[88:89] op_sel:[0,0,0] op_sel_hi:[0,1,1] neg_lo:[1,0,0] neg_hi:[1,0,0]
	v_pk_fma_f32 v[8:9], v[70:71], v[22:23], v[90:91] op_sel:[1,0,0] op_sel_hi:[1,1,1] neg_lo:[1,0,0] neg_hi:[1,0,0]
	s_waitcnt lgkmcnt(0)
	v_pk_mul_f32 v[22:23], v[2:3], v[36:37] op_sel:[0,0] op_sel_hi:[1,0]
	v_pk_mul_f32 v[26:27], v[2:3], v[76:77] op_sel:[0,0] op_sel_hi:[1,0]
	ds_read_b128 v[60:63], v20 offset:6912
	v_pk_fma_f32 v[22:23], v[4:5], v[36:37], v[22:23] op_sel:[0,1,0] op_sel_hi:[1,1,1]
	v_pk_mul_f32 v[84:85], v[4:5], v[76:77] op_sel:[0,1] op_sel_hi:[1,1]
	ds_read_b128 v[64:67], v20 offset:15104
	v_pk_fma_f32 v[22:23], v[6:7], v[38:39], v[22:23] op_sel:[0,0,0] op_sel_hi:[1,0,1]
	v_pk_fma_f32 v[26:27], v[6:7], v[78:79], v[26:27] op_sel:[0,0,0] op_sel_hi:[1,0,1]
	ds_read_b64 v[80:81], v21 offset:47872
	v_pk_fma_f32 v[22:23], v[8:9], v[38:39], v[22:23] op_sel:[0,1,0] op_sel_hi:[1,1,1]
	v_pk_fma_f32 v[84:85], v[8:9], v[78:79], v[84:85] op_sel:[0,1,0] op_sel_hi:[1,1,1]
	ds_read_b128 v[72:75], v20 offset:31488
	v_pk_add_f32 v[26:27], v[26:27], v[84:85]
	ds_read_b128 v[68:71], v20 offset:23296
	ds_read_b128 v[76:79], v20 offset:39680
	v_add_f32_dpp v24, v24, v24 row_ror:12 row_mask:0xf bank_mask:0x5
	v_add_f32_dpp v25, v25, v25 row_ror:4 row_mask:0xf bank_mask:0xa
	v_add_f32_dpp v22, v22, v22 quad_perm:[1,0,3,2] row_mask:0xf bank_mask:0xf
	v_add_f32_dpp v23, v23, v23 quad_perm:[1,0,3,2] row_mask:0xf bank_mask:0xf
	v_pk_mul_f32 v[84:85], v[2:3], v[40:41] op_sel:[0,0] op_sel_hi:[1,0]
	v_pk_mul_f32 v[86:87], v[4:5], v[40:41] op_sel:[0,1] op_sel_hi:[1,1]
	v_mov_b32_dpp v24, v25 quad_perm:[0,1,2,3] row_mask:0xf bank_mask:0xa
	v_add_f32_dpp v22, v22, v22 quad_perm:[2,3,0,1] row_mask:0xf bank_mask:0xf
	v_add_f32_dpp v23, v23, v23 quad_perm:[2,3,0,1] row_mask:0xf bank_mask:0xf
	v_pk_mul_f32 v[88:89], v[6:7], v[42:43] op_sel:[0,0] op_sel_hi:[1,0]
	v_pk_mul_f32 v[90:91], v[8:9], v[42:43] op_sel:[0,1] op_sel_hi:[1,1]
	v_add_f32_dpp v24, v24, v24 row_ror:8 row_mask:0xf bank_mask:0xf
	v_add_f32_dpp v22, v22, v22 row_half_mirror row_mask:0xf bank_mask:0xf
	v_add_f32_dpp v23, v23, v23 row_half_mirror row_mask:0xf bank_mask:0xf
	v_pk_fma_f32 v[84:85], v[48:49], v[56:57], v[84:85] op_sel:[0,0,0] op_sel_hi:[0,1,1]
	v_pk_fma_f32 v[86:87], v[48:49], v[56:57], v[86:87] op_sel:[1,0,0] op_sel_hi:[1,1,1]
	v_add_f32_dpp v24, v24, v24 quad_perm:[1,0,3,2] row_mask:0xf bank_mask:0xf
	v_add_f32_dpp v22, v22, v22 row_mirror row_mask:0xf bank_mask:0xf
	v_add_f32_dpp v23, v23, v23 row_mirror row_mask:0xf bank_mask:0xf
	v_pk_fma_f32 v[88:89], v[50:51], v[56:57], v[88:89] op_sel:[0,0,0] op_sel_hi:[0,1,1]
	v_pk_fma_f32 v[90:91], v[50:51], v[56:57], v[90:91] op_sel:[1,0,0] op_sel_hi:[1,1,1]
	v_add_f32_dpp v24, v24, v24 quad_perm:[2,3,0,1] row_mask:0xf bank_mask:0xf
	v_cndmask_b32_e64 v33, 0, v24, s[0:1]
	v_pk_fma_f32 v[2:3], v[44:45], v[22:23], v[84:85] op_sel:[0,0,0] op_sel_hi:[0,1,1] neg_lo:[1,0,0] neg_hi:[1,0,0]
	v_pk_fma_f32 v[4:5], v[44:45], v[22:23], v[86:87] op_sel:[1,0,0] op_sel_hi:[1,1,1] neg_lo:[1,0,0] neg_hi:[1,0,0]
	v_pk_fma_f32 v[6:7], v[46:47], v[22:23], v[88:89] op_sel:[0,0,0] op_sel_hi:[0,1,1] neg_lo:[1,0,0] neg_hi:[1,0,0]
	v_pk_fma_f32 v[8:9], v[46:47], v[22:23], v[90:91] op_sel:[1,0,0] op_sel_hi:[1,1,1] neg_lo:[1,0,0] neg_hi:[1,0,0]
	s_waitcnt lgkmcnt(0)
	v_pk_mul_f32 v[22:23], v[2:3], v[60:61] op_sel:[0,0] op_sel_hi:[1,0]
	v_pk_mul_f32 v[24:25], v[2:3], v[52:53] op_sel:[0,0] op_sel_hi:[1,0]
	ds_read_b128 v[36:39], v20 offset:7168
	v_pk_fma_f32 v[22:23], v[4:5], v[60:61], v[22:23] op_sel:[0,1,0] op_sel_hi:[1,1,1]
	v_pk_mul_f32 v[84:85], v[4:5], v[52:53] op_sel:[0,1] op_sel_hi:[1,1]
	ds_read_b128 v[40:43], v20 offset:15360
	v_pk_fma_f32 v[22:23], v[6:7], v[62:63], v[22:23] op_sel:[0,0,0] op_sel_hi:[1,0,1]
	v_pk_fma_f32 v[24:25], v[6:7], v[54:55], v[24:25] op_sel:[0,0,0] op_sel_hi:[1,0,1]
	ds_read_b64 v[56:57], v21 offset:48128
	v_pk_fma_f32 v[22:23], v[8:9], v[62:63], v[22:23] op_sel:[0,1,0] op_sel_hi:[1,1,1]
	v_pk_fma_f32 v[84:85], v[8:9], v[54:55], v[84:85] op_sel:[0,1,0] op_sel_hi:[1,1,1]
	ds_read_b128 v[48:51], v20 offset:31744
	v_pk_add_f32 v[24:25], v[24:25], v[84:85]
	ds_read_b128 v[44:47], v20 offset:23552
	ds_read_b128 v[52:55], v20 offset:39936
	v_add_f32_dpp v26, v26, v26 row_ror:12 row_mask:0xf bank_mask:0x5
	v_add_f32_dpp v27, v27, v27 row_ror:4 row_mask:0xf bank_mask:0xa
	v_add_f32_dpp v22, v22, v22 quad_perm:[1,0,3,2] row_mask:0xf bank_mask:0xf
	v_add_f32_dpp v23, v23, v23 quad_perm:[1,0,3,2] row_mask:0xf bank_mask:0xf
	v_pk_mul_f32 v[84:85], v[2:3], v[64:65] op_sel:[0,0] op_sel_hi:[1,0]
	v_pk_mul_f32 v[86:87], v[4:5], v[64:65] op_sel:[0,1] op_sel_hi:[1,1]
	v_mov_b32_dpp v26, v27 quad_perm:[0,1,2,3] row_mask:0xf bank_mask:0xa
	v_add_f32_dpp v22, v22, v22 quad_perm:[2,3,0,1] row_mask:0xf bank_mask:0xf
	v_add_f32_dpp v23, v23, v23 quad_perm:[2,3,0,1] row_mask:0xf bank_mask:0xf
	v_pk_mul_f32 v[88:89], v[6:7], v[66:67] op_sel:[0,0] op_sel_hi:[1,0]
	v_pk_mul_f32 v[90:91], v[8:9], v[66:67] op_sel:[0,1] op_sel_hi:[1,1]
	v_add_f32_dpp v26, v26, v26 row_ror:8 row_mask:0xf bank_mask:0xf
	v_add_f32_dpp v22, v22, v22 row_half_mirror row_mask:0xf bank_mask:0xf
	v_add_f32_dpp v23, v23, v23 row_half_mirror row_mask:0xf bank_mask:0xf
	v_pk_fma_f32 v[84:85], v[72:73], v[80:81], v[84:85] op_sel:[0,0,0] op_sel_hi:[0,1,1]
	v_pk_fma_f32 v[86:87], v[72:73], v[80:81], v[86:87] op_sel:[1,0,0] op_sel_hi:[1,1,1]
	v_add_f32_dpp v26, v26, v26 quad_perm:[1,0,3,2] row_mask:0xf bank_mask:0xf
	v_add_f32_dpp v22, v22, v22 row_mirror row_mask:0xf bank_mask:0xf
	v_add_f32_dpp v23, v23, v23 row_mirror row_mask:0xf bank_mask:0xf
	v_pk_fma_f32 v[88:89], v[74:75], v[80:81], v[88:89] op_sel:[0,0,0] op_sel_hi:[0,1,1]
	v_pk_fma_f32 v[90:91], v[74:75], v[80:81], v[90:91] op_sel:[1,0,0] op_sel_hi:[1,1,1]
	v_add_f32_dpp v26, v26, v26 quad_perm:[2,3,0,1] row_mask:0xf bank_mask:0xf
	v_cndmask_b32_e64 v33, v33, v26, s[6:7]
	v_pk_fma_f32 v[2:3], v[68:69], v[22:23], v[84:85] op_sel:[0,0,0] op_sel_hi:[0,1,1] neg_lo:[1,0,0] neg_hi:[1,0,0]
	v_pk_fma_f32 v[4:5], v[68:69], v[22:23], v[86:87] op_sel:[1,0,0] op_sel_hi:[1,1,1] neg_lo:[1,0,0] neg_hi:[1,0,0]
	v_pk_fma_f32 v[6:7], v[70:71], v[22:23], v[88:89] op_sel:[0,0,0] op_sel_hi:[0,1,1] neg_lo:[1,0,0] neg_hi:[1,0,0]
	v_pk_fma_f32 v[8:9], v[70:71], v[22:23], v[90:91] op_sel:[1,0,0] op_sel_hi:[1,1,1] neg_lo:[1,0,0] neg_hi:[1,0,0]
	s_waitcnt lgkmcnt(0)
	v_pk_mul_f32 v[22:23], v[2:3], v[36:37] op_sel:[0,0] op_sel_hi:[1,0]
	v_pk_mul_f32 v[26:27], v[2:3], v[76:77] op_sel:[0,0] op_sel_hi:[1,0]
	ds_read_b128 v[60:63], v20 offset:7424
	v_pk_fma_f32 v[22:23], v[4:5], v[36:37], v[22:23] op_sel:[0,1,0] op_sel_hi:[1,1,1]
	v_pk_mul_f32 v[84:85], v[4:5], v[76:77] op_sel:[0,1] op_sel_hi:[1,1]
	ds_read_b128 v[64:67], v20 offset:15616
	v_pk_fma_f32 v[22:23], v[6:7], v[38:39], v[22:23] op_sel:[0,0,0] op_sel_hi:[1,0,1]
	v_pk_fma_f32 v[26:27], v[6:7], v[78:79], v[26:27] op_sel:[0,0,0] op_sel_hi:[1,0,1]
	ds_read_b64 v[80:81], v21 offset:48384
	v_pk_fma_f32 v[22:23], v[8:9], v[38:39], v[22:23] op_sel:[0,1,0] op_sel_hi:[1,1,1]
	v_pk_fma_f32 v[84:85], v[8:9], v[78:79], v[84:85] op_sel:[0,1,0] op_sel_hi:[1,1,1]
	ds_read_b128 v[72:75], v20 offset:32000
	v_pk_add_f32 v[26:27], v[26:27], v[84:85]
	ds_read_b128 v[68:71], v20 offset:23808
	ds_read_b128 v[76:79], v20 offset:40192
	v_add_f32_dpp v24, v24, v24 row_ror:12 row_mask:0xf bank_mask:0x5
	v_add_f32_dpp v25, v25, v25 row_ror:4 row_mask:0xf bank_mask:0xa
	v_add_f32_dpp v22, v22, v22 quad_perm:[1,0,3,2] row_mask:0xf bank_mask:0xf
	v_add_f32_dpp v23, v23, v23 quad_perm:[1,0,3,2] row_mask:0xf bank_mask:0xf
	v_pk_mul_f32 v[84:85], v[2:3], v[40:41] op_sel:[0,0] op_sel_hi:[1,0]
	v_pk_mul_f32 v[86:87], v[4:5], v[40:41] op_sel:[0,1] op_sel_hi:[1,1]
	v_mov_b32_dpp v24, v25 quad_perm:[0,1,2,3] row_mask:0xf bank_mask:0xa
	v_add_f32_dpp v22, v22, v22 quad_perm:[2,3,0,1] row_mask:0xf bank_mask:0xf
	v_add_f32_dpp v23, v23, v23 quad_perm:[2,3,0,1] row_mask:0xf bank_mask:0xf
	v_pk_mul_f32 v[88:89], v[6:7], v[42:43] op_sel:[0,0] op_sel_hi:[1,0]
	v_pk_mul_f32 v[90:91], v[8:9], v[42:43] op_sel:[0,1] op_sel_hi:[1,1]
	v_add_f32_dpp v24, v24, v24 row_ror:8 row_mask:0xf bank_mask:0xf
	v_add_f32_dpp v22, v22, v22 row_half_mirror row_mask:0xf bank_mask:0xf
	v_add_f32_dpp v23, v23, v23 row_half_mirror row_mask:0xf bank_mask:0xf
	v_pk_fma_f32 v[84:85], v[48:49], v[56:57], v[84:85] op_sel:[0,0,0] op_sel_hi:[0,1,1]
	v_pk_fma_f32 v[86:87], v[48:49], v[56:57], v[86:87] op_sel:[1,0,0] op_sel_hi:[1,1,1]
	v_add_f32_dpp v24, v24, v24 quad_perm:[1,0,3,2] row_mask:0xf bank_mask:0xf
	v_add_f32_dpp v22, v22, v22 row_mirror row_mask:0xf bank_mask:0xf
	v_add_f32_dpp v23, v23, v23 row_mirror row_mask:0xf bank_mask:0xf
	v_pk_fma_f32 v[88:89], v[50:51], v[56:57], v[88:89] op_sel:[0,0,0] op_sel_hi:[0,1,1]
	v_pk_fma_f32 v[90:91], v[50:51], v[56:57], v[90:91] op_sel:[1,0,0] op_sel_hi:[1,1,1]
	v_add_f32_dpp v24, v24, v24 quad_perm:[2,3,0,1] row_mask:0xf bank_mask:0xf
	v_cndmask_b32_e64 v33, v33, v24, s[8:9]
	v_pk_fma_f32 v[2:3], v[44:45], v[22:23], v[84:85] op_sel:[0,0,0] op_sel_hi:[0,1,1] neg_lo:[1,0,0] neg_hi:[1,0,0]
	v_pk_fma_f32 v[4:5], v[44:45], v[22:23], v[86:87] op_sel:[1,0,0] op_sel_hi:[1,1,1] neg_lo:[1,0,0] neg_hi:[1,0,0]
	v_pk_fma_f32 v[6:7], v[46:47], v[22:23], v[88:89] op_sel:[0,0,0] op_sel_hi:[0,1,1] neg_lo:[1,0,0] neg_hi:[1,0,0]
	v_pk_fma_f32 v[8:9], v[46:47], v[22:23], v[90:91] op_sel:[1,0,0] op_sel_hi:[1,1,1] neg_lo:[1,0,0] neg_hi:[1,0,0]
	s_waitcnt lgkmcnt(0)
	v_pk_mul_f32 v[22:23], v[2:3], v[60:61] op_sel:[0,0] op_sel_hi:[1,0]
	v_pk_mul_f32 v[24:25], v[2:3], v[52:53] op_sel:[0,0] op_sel_hi:[1,0]
	ds_read_b128 v[36:39], v20 offset:7680
	v_pk_fma_f32 v[22:23], v[4:5], v[60:61], v[22:23] op_sel:[0,1,0] op_sel_hi:[1,1,1]
	v_pk_mul_f32 v[84:85], v[4:5], v[52:53] op_sel:[0,1] op_sel_hi:[1,1]
	ds_read_b128 v[40:43], v20 offset:15872
	v_pk_fma_f32 v[22:23], v[6:7], v[62:63], v[22:23] op_sel:[0,0,0] op_sel_hi:[1,0,1]
	v_pk_fma_f32 v[24:25], v[6:7], v[54:55], v[24:25] op_sel:[0,0,0] op_sel_hi:[1,0,1]
	ds_read_b64 v[56:57], v21 offset:48640
	v_pk_fma_f32 v[22:23], v[8:9], v[62:63], v[22:23] op_sel:[0,1,0] op_sel_hi:[1,1,1]
	v_pk_fma_f32 v[84:85], v[8:9], v[54:55], v[84:85] op_sel:[0,1,0] op_sel_hi:[1,1,1]
	ds_read_b128 v[48:51], v20 offset:32256
	v_pk_add_f32 v[24:25], v[24:25], v[84:85]
	ds_read_b128 v[44:47], v20 offset:24064
	ds_read_b128 v[52:55], v20 offset:40448
	v_add_f32_dpp v26, v26, v26 row_ror:12 row_mask:0xf bank_mask:0x5
	v_add_f32_dpp v27, v27, v27 row_ror:4 row_mask:0xf bank_mask:0xa
	v_add_f32_dpp v22, v22, v22 quad_perm:[1,0,3,2] row_mask:0xf bank_mask:0xf
	v_add_f32_dpp v23, v23, v23 quad_perm:[1,0,3,2] row_mask:0xf bank_mask:0xf
	v_pk_mul_f32 v[84:85], v[2:3], v[64:65] op_sel:[0,0] op_sel_hi:[1,0]
	v_pk_mul_f32 v[86:87], v[4:5], v[64:65] op_sel:[0,1] op_sel_hi:[1,1]
	v_mov_b32_dpp v26, v27 quad_perm:[0,1,2,3] row_mask:0xf bank_mask:0xa
	v_add_f32_dpp v22, v22, v22 quad_perm:[2,3,0,1] row_mask:0xf bank_mask:0xf
	v_add_f32_dpp v23, v23, v23 quad_perm:[2,3,0,1] row_mask:0xf bank_mask:0xf
	v_pk_mul_f32 v[88:89], v[6:7], v[66:67] op_sel:[0,0] op_sel_hi:[1,0]
	v_pk_mul_f32 v[90:91], v[8:9], v[66:67] op_sel:[0,1] op_sel_hi:[1,1]
	v_add_f32_dpp v26, v26, v26 row_ror:8 row_mask:0xf bank_mask:0xf
	v_add_f32_dpp v22, v22, v22 row_half_mirror row_mask:0xf bank_mask:0xf
	v_add_f32_dpp v23, v23, v23 row_half_mirror row_mask:0xf bank_mask:0xf
	v_pk_fma_f32 v[84:85], v[72:73], v[80:81], v[84:85] op_sel:[0,0,0] op_sel_hi:[0,1,1]
	v_pk_fma_f32 v[86:87], v[72:73], v[80:81], v[86:87] op_sel:[1,0,0] op_sel_hi:[1,1,1]
	v_add_f32_dpp v26, v26, v26 quad_perm:[1,0,3,2] row_mask:0xf bank_mask:0xf
	v_add_f32_dpp v22, v22, v22 row_mirror row_mask:0xf bank_mask:0xf
	v_add_f32_dpp v23, v23, v23 row_mirror row_mask:0xf bank_mask:0xf
	v_pk_fma_f32 v[88:89], v[74:75], v[80:81], v[88:89] op_sel:[0,0,0] op_sel_hi:[0,1,1]
	v_pk_fma_f32 v[90:91], v[74:75], v[80:81], v[90:91] op_sel:[1,0,0] op_sel_hi:[1,1,1]
	v_add_f32_dpp v26, v26, v26 quad_perm:[2,3,0,1] row_mask:0xf bank_mask:0xf
	v_cndmask_b32_e64 v33, v33, v26, s[10:11]
	v_pk_fma_f32 v[2:3], v[68:69], v[22:23], v[84:85] op_sel:[0,0,0] op_sel_hi:[0,1,1] neg_lo:[1,0,0] neg_hi:[1,0,0]
	v_pk_fma_f32 v[4:5], v[68:69], v[22:23], v[86:87] op_sel:[1,0,0] op_sel_hi:[1,1,1] neg_lo:[1,0,0] neg_hi:[1,0,0]
	v_pk_fma_f32 v[6:7], v[70:71], v[22:23], v[88:89] op_sel:[0,0,0] op_sel_hi:[0,1,1] neg_lo:[1,0,0] neg_hi:[1,0,0]
	v_pk_fma_f32 v[8:9], v[70:71], v[22:23], v[90:91] op_sel:[1,0,0] op_sel_hi:[1,1,1] neg_lo:[1,0,0] neg_hi:[1,0,0]
	s_waitcnt lgkmcnt(0)
	v_pk_mul_f32 v[22:23], v[2:3], v[36:37] op_sel:[0,0] op_sel_hi:[1,0]
	v_pk_mul_f32 v[26:27], v[2:3], v[76:77] op_sel:[0,0] op_sel_hi:[1,0]
	ds_read_b128 v[60:63], v20 offset:7936
	v_pk_fma_f32 v[22:23], v[4:5], v[36:37], v[22:23] op_sel:[0,1,0] op_sel_hi:[1,1,1]
	v_pk_mul_f32 v[84:85], v[4:5], v[76:77] op_sel:[0,1] op_sel_hi:[1,1]
	ds_read_b128 v[64:67], v20 offset:16128
	v_pk_fma_f32 v[22:23], v[6:7], v[38:39], v[22:23] op_sel:[0,0,0] op_sel_hi:[1,0,1]
	v_pk_fma_f32 v[26:27], v[6:7], v[78:79], v[26:27] op_sel:[0,0,0] op_sel_hi:[1,0,1]
	ds_read_b64 v[80:81], v21 offset:48896
	v_pk_fma_f32 v[22:23], v[8:9], v[38:39], v[22:23] op_sel:[0,1,0] op_sel_hi:[1,1,1]
	v_pk_fma_f32 v[84:85], v[8:9], v[78:79], v[84:85] op_sel:[0,1,0] op_sel_hi:[1,1,1]
	ds_read_b128 v[72:75], v20 offset:32512
	v_pk_add_f32 v[26:27], v[26:27], v[84:85]
	ds_read_b128 v[68:71], v20 offset:24320
	ds_read_b128 v[76:79], v20 offset:40704
	v_add_f32_dpp v24, v24, v24 row_ror:12 row_mask:0xf bank_mask:0x5
	v_add_f32_dpp v25, v25, v25 row_ror:4 row_mask:0xf bank_mask:0xa
	v_add_f32_dpp v22, v22, v22 quad_perm:[1,0,3,2] row_mask:0xf bank_mask:0xf
	v_add_f32_dpp v23, v23, v23 quad_perm:[1,0,3,2] row_mask:0xf bank_mask:0xf
	v_pk_mul_f32 v[84:85], v[2:3], v[40:41] op_sel:[0,0] op_sel_hi:[1,0]
	v_pk_mul_f32 v[86:87], v[4:5], v[40:41] op_sel:[0,1] op_sel_hi:[1,1]
	v_mov_b32_dpp v24, v25 quad_perm:[0,1,2,3] row_mask:0xf bank_mask:0xa
	v_add_f32_dpp v22, v22, v22 quad_perm:[2,3,0,1] row_mask:0xf bank_mask:0xf
	v_add_f32_dpp v23, v23, v23 quad_perm:[2,3,0,1] row_mask:0xf bank_mask:0xf
	v_pk_mul_f32 v[88:89], v[6:7], v[42:43] op_sel:[0,0] op_sel_hi:[1,0]
	v_pk_mul_f32 v[90:91], v[8:9], v[42:43] op_sel:[0,1] op_sel_hi:[1,1]
	v_add_f32_dpp v24, v24, v24 row_ror:8 row_mask:0xf bank_mask:0xf
	v_add_f32_dpp v22, v22, v22 row_half_mirror row_mask:0xf bank_mask:0xf
	v_add_f32_dpp v23, v23, v23 row_half_mirror row_mask:0xf bank_mask:0xf
	v_pk_fma_f32 v[84:85], v[48:49], v[56:57], v[84:85] op_sel:[0,0,0] op_sel_hi:[0,1,1]
	v_pk_fma_f32 v[86:87], v[48:49], v[56:57], v[86:87] op_sel:[1,0,0] op_sel_hi:[1,1,1]
	v_add_f32_dpp v24, v24, v24 quad_perm:[1,0,3,2] row_mask:0xf bank_mask:0xf
	v_add_f32_dpp v22, v22, v22 row_mirror row_mask:0xf bank_mask:0xf
	v_add_f32_dpp v23, v23, v23 row_mirror row_mask:0xf bank_mask:0xf
	v_pk_fma_f32 v[88:89], v[50:51], v[56:57], v[88:89] op_sel:[0,0,0] op_sel_hi:[0,1,1]
	v_pk_fma_f32 v[90:91], v[50:51], v[56:57], v[90:91] op_sel:[1,0,0] op_sel_hi:[1,1,1]
	v_add_f32_dpp v24, v24, v24 quad_perm:[2,3,0,1] row_mask:0xf bank_mask:0xf
	v_cndmask_b32_e64 v33, v33, v24, s[12:13]
	v_pk_fma_f32 v[2:3], v[44:45], v[22:23], v[84:85] op_sel:[0,0,0] op_sel_hi:[0,1,1] neg_lo:[1,0,0] neg_hi:[1,0,0]
	v_pk_fma_f32 v[4:5], v[44:45], v[22:23], v[86:87] op_sel:[1,0,0] op_sel_hi:[1,1,1] neg_lo:[1,0,0] neg_hi:[1,0,0]
	v_pk_fma_f32 v[6:7], v[46:47], v[22:23], v[88:89] op_sel:[0,0,0] op_sel_hi:[0,1,1] neg_lo:[1,0,0] neg_hi:[1,0,0]
	v_pk_fma_f32 v[8:9], v[46:47], v[22:23], v[90:91] op_sel:[1,0,0] op_sel_hi:[1,1,1] neg_lo:[1,0,0] neg_hi:[1,0,0]
	s_waitcnt lgkmcnt(0)
	v_pk_mul_f32 v[22:23], v[2:3], v[60:61] op_sel:[0,0] op_sel_hi:[1,0]
	v_pk_mul_f32 v[24:25], v[2:3], v[52:53] op_sel:[0,0] op_sel_hi:[1,0]
	v_pk_fma_f32 v[22:23], v[4:5], v[60:61], v[22:23] op_sel:[0,1,0] op_sel_hi:[1,1,1]
	v_pk_mul_f32 v[84:85], v[4:5], v[52:53] op_sel:[0,1] op_sel_hi:[1,1]
	v_pk_fma_f32 v[22:23], v[6:7], v[62:63], v[22:23] op_sel:[0,0,0] op_sel_hi:[1,0,1]
	v_pk_fma_f32 v[24:25], v[6:7], v[54:55], v[24:25] op_sel:[0,0,0] op_sel_hi:[1,0,1]
	v_pk_fma_f32 v[22:23], v[8:9], v[62:63], v[22:23] op_sel:[0,1,0] op_sel_hi:[1,1,1]
	v_pk_fma_f32 v[84:85], v[8:9], v[54:55], v[84:85] op_sel:[0,1,0] op_sel_hi:[1,1,1]
	v_pk_add_f32 v[24:25], v[24:25], v[84:85]
	v_add_f32_dpp v26, v26, v26 row_ror:12 row_mask:0xf bank_mask:0x5
	v_add_f32_dpp v27, v27, v27 row_ror:4 row_mask:0xf bank_mask:0xa
	v_add_f32_dpp v22, v22, v22 quad_perm:[1,0,3,2] row_mask:0xf bank_mask:0xf
	v_add_f32_dpp v23, v23, v23 quad_perm:[1,0,3,2] row_mask:0xf bank_mask:0xf
	v_pk_mul_f32 v[84:85], v[2:3], v[64:65] op_sel:[0,0] op_sel_hi:[1,0]
	v_pk_mul_f32 v[86:87], v[4:5], v[64:65] op_sel:[0,1] op_sel_hi:[1,1]
	v_mov_b32_dpp v26, v27 quad_perm:[0,1,2,3] row_mask:0xf bank_mask:0xa
	v_add_f32_dpp v22, v22, v22 quad_perm:[2,3,0,1] row_mask:0xf bank_mask:0xf
	v_add_f32_dpp v23, v23, v23 quad_perm:[2,3,0,1] row_mask:0xf bank_mask:0xf
	v_pk_mul_f32 v[88:89], v[6:7], v[66:67] op_sel:[0,0] op_sel_hi:[1,0]
	v_pk_mul_f32 v[90:91], v[8:9], v[66:67] op_sel:[0,1] op_sel_hi:[1,1]
	v_add_f32_dpp v26, v26, v26 row_ror:8 row_mask:0xf bank_mask:0xf
	v_add_f32_dpp v22, v22, v22 row_half_mirror row_mask:0xf bank_mask:0xf
	v_add_f32_dpp v23, v23, v23 row_half_mirror row_mask:0xf bank_mask:0xf
	v_pk_fma_f32 v[84:85], v[72:73], v[80:81], v[84:85] op_sel:[0,0,0] op_sel_hi:[0,1,1]
	v_pk_fma_f32 v[86:87], v[72:73], v[80:81], v[86:87] op_sel:[1,0,0] op_sel_hi:[1,1,1]
	v_add_f32_dpp v26, v26, v26 quad_perm:[1,0,3,2] row_mask:0xf bank_mask:0xf
	v_add_f32_dpp v22, v22, v22 row_mirror row_mask:0xf bank_mask:0xf
	v_add_f32_dpp v23, v23, v23 row_mirror row_mask:0xf bank_mask:0xf
	v_pk_fma_f32 v[88:89], v[74:75], v[80:81], v[88:89] op_sel:[0,0,0] op_sel_hi:[0,1,1]
	v_pk_fma_f32 v[90:91], v[74:75], v[80:81], v[90:91] op_sel:[1,0,0] op_sel_hi:[1,1,1]
	v_add_f32_dpp v26, v26, v26 quad_perm:[2,3,0,1] row_mask:0xf bank_mask:0xf
	v_cndmask_b32_e64 v33, v33, v26, s[14:15]
	v_pk_fma_f32 v[2:3], v[68:69], v[22:23], v[84:85] op_sel:[0,0,0] op_sel_hi:[0,1,1] neg_lo:[1,0,0] neg_hi:[1,0,0]
	v_pk_fma_f32 v[4:5], v[68:69], v[22:23], v[86:87] op_sel:[1,0,0] op_sel_hi:[1,1,1] neg_lo:[1,0,0] neg_hi:[1,0,0]
	v_pk_fma_f32 v[6:7], v[70:71], v[22:23], v[88:89] op_sel:[0,0,0] op_sel_hi:[0,1,1] neg_lo:[1,0,0] neg_hi:[1,0,0]
	v_pk_fma_f32 v[8:9], v[70:71], v[22:23], v[90:91] op_sel:[1,0,0] op_sel_hi:[1,1,1] neg_lo:[1,0,0] neg_hi:[1,0,0]
	s_waitcnt lgkmcnt(0)
	v_add_f32_dpp v24, v24, v24 row_ror:12 row_mask:0xf bank_mask:0x5
	v_add_f32_dpp v25, v25, v25 row_ror:4 row_mask:0xf bank_mask:0xa
	s_nop 1
	v_mov_b32_dpp v24, v25 quad_perm:[0,1,2,3] row_mask:0xf bank_mask:0xa
	s_nop 1
	v_add_f32_dpp v24, v24, v24 row_ror:8 row_mask:0xf bank_mask:0xf
	s_nop 1
	v_add_f32_dpp v24, v24, v24 quad_perm:[1,0,3,2] row_mask:0xf bank_mask:0xf
	s_nop 1
	v_add_f32_dpp v24, v24, v24 quad_perm:[2,3,0,1] row_mask:0xf bank_mask:0xf
	v_cndmask_b32_e64 v33, v33, v24, s[16:17]
	v_pk_mul_f32 v[26:27], v[2:3], v[76:77] op_sel:[0,0] op_sel_hi:[1,0]
	v_pk_mul_f32 v[84:85], v[4:5], v[76:77] op_sel:[0,1] op_sel_hi:[1,1]
	v_pk_fma_f32 v[26:27], v[6:7], v[78:79], v[26:27] op_sel:[0,0,0] op_sel_hi:[1,0,1]
	v_pk_fma_f32 v[84:85], v[8:9], v[78:79], v[84:85] op_sel:[0,1,0] op_sel_hi:[1,1,1]
	v_pk_add_f32 v[26:27], v[26:27], v[84:85]
	s_nop 1
	v_add_f32_dpp v26, v26, v26 row_ror:12 row_mask:0xf bank_mask:0x5
	v_add_f32_dpp v27, v27, v27 row_ror:4 row_mask:0xf bank_mask:0xa
	s_nop 1
	v_mov_b32_dpp v26, v27 quad_perm:[0,1,2,3] row_mask:0xf bank_mask:0xa
	s_nop 1
	v_add_f32_dpp v26, v26, v26 row_ror:8 row_mask:0xf bank_mask:0xf
	s_nop 1
	v_add_f32_dpp v26, v26, v26 quad_perm:[1,0,3,2] row_mask:0xf bank_mask:0xf
	s_nop 1
	v_add_f32_dpp v26, v26, v26 quad_perm:[2,3,0,1] row_mask:0xf bank_mask:0xf
	v_cndmask_b32_e32 v33, v33, v26, vcc
	v_lshl_add_u32 v35, s23, 12, v11
	s_add_i32 s22, s22, 1
	ds_write2st64_b32 v35, v30, v31 offset1:4
	ds_write2st64_b32 v35, v32, v33 offset0:8 offset1:12
	s_cmp_eq_u32 s22, 64
	s_waitcnt lgkmcnt(0)
	s_barrier
	s_cbranch_scc0 .LBB0_1750
	s_lshl_b32 s0, s18, 4
	s_or_b32 s0, s0, s26
	s_ashr_i32 s1, s0, 31
	s_lshl_b64 s[0:1], s[0:1], 6
	s_lshl_b32 s2, s27, 5
	s_or_b32 s0, s0, s2
	v_or_b32_e32 v12, s0, v1
	v_mov_b32_e32 v13, s1
	v_lshlrev_b64 v[12:13], 8, v[12:13]
	v_lshl_add_u64 v[12:13], s[82:83], 0, v[12:13]
	v_mov_b32_e32 v11, 0
	v_lshl_add_u64 v[10:11], v[12:13], 0, v[10:11]
	s_mov_b64 s[0:1], 0x4100000
	v_lshl_add_u64 v[12:13], v[10:11], 0, s[0:1]
	v_add_co_u32_e32 v10, vcc, 0x4100000, v10
	s_nop 1
	v_addc_co_u32_e32 v11, vcc, 0, v11, vcc
	v_mov_b32_e32 v14, v2
	v_mov_b32_e32 v15, v4
	v_mov_b32_e32 v16, v6
	v_mov_b32_e32 v17, v8
	v_mov_b32_e32 v18, v3
	v_mov_b32_e32 v19, v5
	v_mov_b32_e32 v20, v7
	v_mov_b32_e32 v21, v9
	global_store_dwordx4 v[10:11], v[14:17], off
	global_store_dwordx4 v[12:13], v[18:21], off offset:256

.Lprod_noconv:
	s_cmp_gt_u32 s5, 61
	s_cbranch_scc1 .Lprod_noload
	s_add_u32 s40, s34, 0xd3d4000
	s_addc_u32 s41, s35, 0
	global_load_ushort v100, v44, s[40:41] offset:1536
	global_load_ushort v101, v44, s[40:41] offset:3584
	s_add_u32 s42, s34, 0xd3d5000
	s_addc_u32 s43, s35, 0
	global_load_ushort v102, v44, s[42:43] offset:1536
	s_add_u32 s40, s34, 0xd3da000
	s_addc_u32 s41, s35, 0
	global_load_ushort v103, v44, s[40:41] offset:512
	global_load_ushort v104, v44, s[40:41] offset:2560
	s_add_u32 s42, s34, 0xd3db000
	s_addc_u32 s43, s35, 0
	global_load_ushort v105, v44, s[42:43] offset:512
	s_add_u32 s40, s34, 0xd3df000
	s_addc_u32 s41, s35, 0
	global_load_ushort v106, v44, s[40:41] offset:3584
	s_add_u32 s42, s34, 0xd3e0000
	s_addc_u32 s43, s35, 0
	global_load_ushort v107, v44, s[42:43] offset:1536
	global_load_ushort v108, v44, s[42:43] offset:3584
	s_add_u32 s40, s34, 0xd3e5000
	s_addc_u32 s41, s35, 0
	global_load_ushort v109, v44, s[40:41] offset:2560
	s_add_u32 s42, s34, 0xd3e6000
	s_addc_u32 s43, s35, 0
	global_load_ushort v110, v44, s[42:43] offset:512
	global_load_ushort v111, v44, s[42:43] offset:2560
	s_add_u32 s40, s34, 0xd3eb000
	s_addc_u32 s41, s35, 0
	global_load_ushort v112, v44, s[40:41] offset:1536
	global_load_ushort v113, v44, s[40:41] offset:3584
	s_add_u32 s42, s34, 0xd3ec000
	s_addc_u32 s43, s35, 0
	global_load_ushort v114, v44, s[42:43] offset:1536
	s_add_u32 s40, s34, 0xd3f1000
	s_addc_u32 s41, s35, 0
	global_load_ushort v115, v44, s[40:41] offset:512
	global_load_ushort v116, v44, s[40:41] offset:2560
	s_add_u32 s42, s34, 0xd3f2000
	s_addc_u32 s43, s35, 0
	global_load_ushort v117, v44, s[42:43] offset:512
	s_add_u32 s40, s34, 0xd3f6000
	s_addc_u32 s41, s35, 0
	global_load_ushort v118, v44, s[40:41] offset:3584
	s_add_u32 s42, s34, 0xd3f7000
	s_addc_u32 s43, s35, 0
	global_load_ushort v119, v44, s[42:43] offset:1536
	global_load_ushort v120, v44, s[42:43] offset:3584
	s_add_u32 s40, s34, 0xd3fc000
	s_addc_u32 s41, s35, 0
	global_load_ushort v121, v44, s[40:41] offset:2560
	s_add_u32 s42, s34, 0xd3fd000
	s_addc_u32 s43, s35, 0
	global_load_ushort v122, v44, s[42:43] offset:512
	global_load_ushort v123, v44, s[42:43] offset:2560
	s_add_u32 s40, s34, 0xd403000
	s_addc_u32 s41, s35, 0
	global_load_ushort v124, v44, s[40:41] offset:1536
	s_add_u32 s42, s34, 0xd402000
	s_addc_u32 s43, s35, 0
	global_load_ushort v125, v44, s[42:43] offset:3584
	global_load_ushort v126, v44, s[42:43] offset:1536
	s_add_u32 s40, s34, 0x1b202000
	s_addc_u32 s41, s35, 0
	s_add_u32 s42, s34, 0x19102000
	s_addc_u32 s43, s35, 0
	v_lshlrev_b32_e32 v158, 2, v48
	global_load_dword v130, v46, s[40:41] offset:512
	global_load_dword v131, v46, s[42:43] offset:512
	s_add_u32 s40, s14, 0x1000
	s_addc_u32 s41, s15, 0
	s_add_u32 s42, s12, 0x1000
	s_addc_u32 s43, s13, 0
	global_load_dword v132, v158, s[40:41]
	global_load_dword v133, v158, s[42:43]
	s_add_u32 s40, s14, 0x2000
	s_addc_u32 s41, s15, 0
	s_add_u32 s42, s12, 0x2000
	s_addc_u32 s43, s13, 0
	global_load_dword v134, v158, s[40:41]
	global_load_dword v135, v158, s[42:43]
	s_add_u32 s40, s14, 0x3000
	s_addc_u32 s41, s15, 0
	s_add_u32 s42, s12, 0x3000
	s_addc_u32 s43, s13, 0
	global_load_dword v136, v158, s[40:41]
	global_load_dword v137, v158, s[42:43]
	s_add_u32 s40, s14, 0x4000
	s_addc_u32 s41, s15, 0
	s_add_u32 s42, s12, 0x4000
	s_addc_u32 s43, s13, 0
	global_load_dword v138, v158, s[40:41]
	global_load_dword v139, v158, s[42:43]
	s_add_u32 s40, s14, 0x5000
	s_addc_u32 s41, s15, 0
	s_add_u32 s42, s12, 0x5000
	s_addc_u32 s43, s13, 0
	global_load_dword v140, v158, s[40:41]
	global_load_dword v141, v158, s[42:43]
	s_add_u32 s40, s14, 0x6000
	s_addc_u32 s41, s15, 0
	s_add_u32 s42, s12, 0x6000
	s_addc_u32 s43, s13, 0
	global_load_dword v142, v158, s[40:41]
	global_load_dword v143, v158, s[42:43]
	s_add_u32 s40, s14, 0x7000
	s_addc_u32 s41, s15, 0
	s_add_u32 s42, s12, 0x7000
	s_addc_u32 s43, s13, 0
	global_load_dword v144, v158, s[40:41]
	global_load_dword v145, v158, s[42:43]
